# conv tap loop reads two U rows per LDS instruction (ds_read2st64) and broadcasts lo or hi element in the packed FMAs
# speedup vs baseline: 1.0073x; 1.0065x over previous
; #define LAS __attribute__((address_space(3)))
;     static __device__ __forceinline__ void run(float (&acc)[32], const float (&wv)[31], const LAS float* U, int rb, int cch) {
;         const float uv = U[ring94(ring94(rb + S)) * 256 + cch];
; #pragma unroll
;         for (int o = 0; o < 32; ++o) { constexpr int dummy = 0; const int kk = S - o + dummy; if (kk >= 0 && kk <= 30) acc[o] += wv[kk] * uv; }
;         ConvStep<S + 1>::run(acc, wv, U, rb, cch);
;     }
; __device__ __forceinline__ void conv_loop(unsigned char* ws_, const float* const* in_, int l_, LAS unsigned char* lds, int tid, int bid, int G) {
;     ...
;             float acc[32];
; #pragma unroll
;             for (int o = 0; o < 32; ++o) acc[o] = bias;
;             const int rb = base + 32 * half;
;             ConvStep<0>::run(acc, wv, U, rb, cch);
.LBB0_302:
	v_lshl_add_u32 v231, v103, 10, v104
	v_lshl_add_u64 v[46:47], v[46:47], 0, s[0:1]
	v_lshl_add_u64 v[64:65], v[64:65], 0, s[0:1]
	v_lshl_add_u64 v[66:67], v[66:67], 0, s[0:1]
	v_lshl_add_u64 v[68:69], v[68:69], 0, s[0:1]
	s_mov_b32 s2, 0x1e500000
	v_mul_u32_u24_e32 v229, 0x1e0, v103
	v_add_u32_e32 v229, v229, v104
	v_add_u32_e32 v230, 0x10000, v229
	ds_read2st64_b32 v[232:233], v231 offset0:0 offset1:4
	ds_read2st64_b32 v[234:235], v231 offset0:8 offset1:12
	ds_read2st64_b32 v[236:237], v231 offset0:16 offset1:20
	ds_read2st64_b32 v[238:239], v231 offset0:24 offset1:28
	v_mov_b32_e32 v192, v73
	v_mov_b32_e32 v193, v74
	v_mov_b32_e32 v194, v75
	v_mov_b32_e32 v195, v76
	v_mov_b32_e32 v196, v77
	v_mov_b32_e32 v197, v78
	v_mov_b32_e32 v198, v79
	v_mov_b32_e32 v199, v80
	v_mov_b32_e32 v200, v81
	v_mov_b32_e32 v201, v82
	v_mov_b32_e32 v202, v83
	v_mov_b32_e32 v203, v84
	v_mov_b32_e32 v204, v85
	v_mov_b32_e32 v205, v86
	v_mov_b32_e32 v206, v87
	v_mov_b32_e32 v207, v88
	v_mov_b32_e32 v208, v89
	v_mov_b32_e32 v209, v90
	v_mov_b32_e32 v210, v91
	v_mov_b32_e32 v211, v92
	v_mov_b32_e32 v212, v93
	v_mov_b32_e32 v213, v94
	v_mov_b32_e32 v166, v95
	v_mov_b32_e32 v167, v96
	v_mov_b32_e32 v168, v97
	v_mov_b32_e32 v169, v98
	v_mov_b32_e32 v170, v99
	v_mov_b32_e32 v171, v100
	v_mov_b32_e32 v172, v101
	v_mov_b32_e32 v173, v1
	v_mov_b32_e32 v124, v51
	v_mov_b32_e32 v125, v51
	v_mov_b32_e32 v126, v51
	v_mov_b32_e32 v127, v51
	v_mov_b32_e32 v128, v51
	v_mov_b32_e32 v129, v51
	v_mov_b32_e32 v130, v51
	v_mov_b32_e32 v131, v51
	v_mov_b32_e32 v132, v51
	v_mov_b32_e32 v133, v51
	v_mov_b32_e32 v134, v51
	v_mov_b32_e32 v135, v51
	v_mov_b32_e32 v136, v51
	v_mov_b32_e32 v137, v51
	v_mov_b32_e32 v148, v51
	v_mov_b32_e32 v149, v51
	v_mov_b32_e32 v150, v51
	v_mov_b32_e32 v151, v51
	v_mov_b32_e32 v152, v51
	v_mov_b32_e32 v153, v51
	v_mov_b32_e32 v154, v51
	v_mov_b32_e32 v155, v51
	v_mov_b32_e32 v156, v51
	v_mov_b32_e32 v157, v51
	v_mov_b32_e32 v158, v51
	v_mov_b32_e32 v159, v51
	v_mov_b32_e32 v160, v51
	v_mov_b32_e32 v161, v51
	v_mov_b32_e32 v162, v51
	v_mov_b32_e32 v163, v51
	v_mov_b32_e32 v164, v51
	v_mov_b32_e32 v165, v51
	ds_read2st64_b32 v[240:241], v231 offset0:32 offset1:36
	s_waitcnt lgkmcnt(4)
	v_fmac_f32_e32 v124, v1, v232
	v_pk_fma_f32 v[124:125], v[172:173], v[232:233], v[124:125] op_sel:[0,1,0]
	ds_read2st64_b32 v[232:233], v231 offset0:40 offset1:44
	s_waitcnt lgkmcnt(4)
	v_pk_fma_f32 v[124:125], v[100:101], v[234:235], v[124:125] op_sel_hi:[1,0,1]
	v_fmac_f32_e32 v126, v1, v234
	v_pk_fma_f32 v[124:125], v[170:171], v[234:235], v[124:125] op_sel:[0,1,0]
	v_pk_fma_f32 v[126:127], v[172:173], v[234:235], v[126:127] op_sel:[0,1,0]
	ds_read2st64_b32 v[234:235], v231 offset0:48 offset1:52
	s_waitcnt lgkmcnt(4)
	v_pk_fma_f32 v[124:125], v[98:99], v[236:237], v[124:125] op_sel_hi:[1,0,1]
	v_pk_fma_f32 v[126:127], v[100:101], v[236:237], v[126:127] op_sel_hi:[1,0,1]
	v_fmac_f32_e32 v128, v1, v236
	v_pk_fma_f32 v[124:125], v[168:169], v[236:237], v[124:125] op_sel:[0,1,0]
	v_pk_fma_f32 v[126:127], v[170:171], v[236:237], v[126:127] op_sel:[0,1,0]
	v_pk_fma_f32 v[128:129], v[172:173], v[236:237], v[128:129] op_sel:[0,1,0]
	ds_read2st64_b32 v[236:237], v231 offset0:56 offset1:60
	s_waitcnt lgkmcnt(4)
	v_pk_fma_f32 v[124:125], v[96:97], v[238:239], v[124:125] op_sel_hi:[1,0,1]
	v_pk_fma_f32 v[126:127], v[98:99], v[238:239], v[126:127] op_sel_hi:[1,0,1]
	v_pk_fma_f32 v[128:129], v[100:101], v[238:239], v[128:129] op_sel_hi:[1,0,1]
	v_fmac_f32_e32 v130, v1, v238
	v_pk_fma_f32 v[124:125], v[166:167], v[238:239], v[124:125] op_sel:[0,1,0]
	v_pk_fma_f32 v[126:127], v[168:169], v[238:239], v[126:127] op_sel:[0,1,0]
	v_pk_fma_f32 v[128:129], v[170:171], v[238:239], v[128:129] op_sel:[0,1,0]
	v_pk_fma_f32 v[130:131], v[172:173], v[238:239], v[130:131] op_sel:[0,1,0]
	ds_read2st64_b32 v[238:239], v231 offset0:64 offset1:68
	s_waitcnt lgkmcnt(4)
	v_pk_fma_f32 v[124:125], v[94:95], v[240:241], v[124:125] op_sel_hi:[1,0,1]
	v_pk_fma_f32 v[126:127], v[96:97], v[240:241], v[126:127] op_sel_hi:[1,0,1]
	v_pk_fma_f32 v[128:129], v[98:99], v[240:241], v[128:129] op_sel_hi:[1,0,1]
	v_pk_fma_f32 v[130:131], v[100:101], v[240:241], v[130:131] op_sel_hi:[1,0,1]
	v_fmac_f32_e32 v132, v1, v240
	v_pk_fma_f32 v[124:125], v[212:213], v[240:241], v[124:125] op_sel:[0,1,0]
	v_pk_fma_f32 v[126:127], v[166:167], v[240:241], v[126:127] op_sel:[0,1,0]
	v_pk_fma_f32 v[128:129], v[168:169], v[240:241], v[128:129] op_sel:[0,1,0]
	v_pk_fma_f32 v[130:131], v[170:171], v[240:241], v[130:131] op_sel:[0,1,0]
	v_pk_fma_f32 v[132:133], v[172:173], v[240:241], v[132:133] op_sel:[0,1,0]
	ds_read2st64_b32 v[240:241], v231 offset0:72 offset1:76
	s_waitcnt lgkmcnt(4)
	v_pk_fma_f32 v[124:125], v[92:93], v[232:233], v[124:125] op_sel_hi:[1,0,1]
	v_pk_fma_f32 v[126:127], v[94:95], v[232:233], v[126:127] op_sel_hi:[1,0,1]
	v_pk_fma_f32 v[128:129], v[96:97], v[232:233], v[128:129] op_sel_hi:[1,0,1]
	v_pk_fma_f32 v[130:131], v[98:99], v[232:233], v[130:131] op_sel_hi:[1,0,1]
	v_pk_fma_f32 v[132:133], v[100:101], v[232:233], v[132:133] op_sel_hi:[1,0,1]
	v_fmac_f32_e32 v134, v1, v232
	v_pk_fma_f32 v[124:125], v[210:211], v[232:233], v[124:125] op_sel:[0,1,0]
	v_pk_fma_f32 v[126:127], v[212:213], v[232:233], v[126:127] op_sel:[0,1,0]
	v_pk_fma_f32 v[128:129], v[166:167], v[232:233], v[128:129] op_sel:[0,1,0]
	v_pk_fma_f32 v[130:131], v[168:169], v[232:233], v[130:131] op_sel:[0,1,0]
	v_pk_fma_f32 v[132:133], v[170:171], v[232:233], v[132:133] op_sel:[0,1,0]
	v_pk_fma_f32 v[134:135], v[172:173], v[232:233], v[134:135] op_sel:[0,1,0]
	ds_read2st64_b32 v[232:233], v231 offset0:80 offset1:84
	s_waitcnt lgkmcnt(4)
; #define LAS __attribute__((address_space(3)))
;     static __device__ __forceinline__ void run(float (&acc)[32], const float (&wv)[31], const LAS float* U, int rb, int cch) {
;         const float uv = U[ring94(ring94(rb + S)) * 256 + cch];
; #pragma unroll
;         for (int o = 0; o < 32; ++o) { constexpr int dummy = 0; const int kk = S - o + dummy; if (kk >= 0 && kk <= 30) acc[o] += wv[kk] * uv; }
	v_pk_fma_f32 v[124:125], v[90:91], v[234:235], v[124:125] op_sel_hi:[1,0,1]
	v_pk_fma_f32 v[126:127], v[92:93], v[234:235], v[126:127] op_sel_hi:[1,0,1]
	v_pk_fma_f32 v[128:129], v[94:95], v[234:235], v[128:129] op_sel_hi:[1,0,1]
	v_pk_fma_f32 v[130:131], v[96:97], v[234:235], v[130:131] op_sel_hi:[1,0,1]
	v_pk_fma_f32 v[132:133], v[98:99], v[234:235], v[132:133] op_sel_hi:[1,0,1]
	v_pk_fma_f32 v[134:135], v[100:101], v[234:235], v[134:135] op_sel_hi:[1,0,1]
	v_fmac_f32_e32 v136, v1, v234
	v_pk_fma_f32 v[124:125], v[208:209], v[234:235], v[124:125] op_sel:[0,1,0]
	v_pk_fma_f32 v[126:127], v[210:211], v[234:235], v[126:127] op_sel:[0,1,0]
	v_pk_fma_f32 v[128:129], v[212:213], v[234:235], v[128:129] op_sel:[0,1,0]
	v_pk_fma_f32 v[130:131], v[166:167], v[234:235], v[130:131] op_sel:[0,1,0]
	v_pk_fma_f32 v[132:133], v[168:169], v[234:235], v[132:133] op_sel:[0,1,0]
	v_pk_fma_f32 v[134:135], v[170:171], v[234:235], v[134:135] op_sel:[0,1,0]
	v_pk_fma_f32 v[136:137], v[172:173], v[234:235], v[136:137] op_sel:[0,1,0]
	ds_read2st64_b32 v[234:235], v231 offset0:88 offset1:92
	s_waitcnt lgkmcnt(4)
	v_pk_fma_f32 v[124:125], v[88:89], v[236:237], v[124:125] op_sel_hi:[1,0,1]
	v_pk_fma_f32 v[126:127], v[90:91], v[236:237], v[126:127] op_sel_hi:[1,0,1]
	v_pk_fma_f32 v[128:129], v[92:93], v[236:237], v[128:129] op_sel_hi:[1,0,1]
	v_pk_fma_f32 v[130:131], v[94:95], v[236:237], v[130:131] op_sel_hi:[1,0,1]
	v_pk_fma_f32 v[132:133], v[96:97], v[236:237], v[132:133] op_sel_hi:[1,0,1]
	v_pk_fma_f32 v[134:135], v[98:99], v[236:237], v[134:135] op_sel_hi:[1,0,1]
	v_pk_fma_f32 v[136:137], v[100:101], v[236:237], v[136:137] op_sel_hi:[1,0,1]
	v_fmac_f32_e32 v148, v1, v236
	v_pk_fma_f32 v[124:125], v[206:207], v[236:237], v[124:125] op_sel:[0,1,0]
	v_pk_fma_f32 v[126:127], v[208:209], v[236:237], v[126:127] op_sel:[0,1,0]
	v_pk_fma_f32 v[128:129], v[210:211], v[236:237], v[128:129] op_sel:[0,1,0]
	v_pk_fma_f32 v[130:131], v[212:213], v[236:237], v[130:131] op_sel:[0,1,0]
	v_pk_fma_f32 v[132:133], v[166:167], v[236:237], v[132:133] op_sel:[0,1,0]
	v_pk_fma_f32 v[134:135], v[168:169], v[236:237], v[134:135] op_sel:[0,1,0]
	v_pk_fma_f32 v[136:137], v[170:171], v[236:237], v[136:137] op_sel:[0,1,0]
	v_pk_fma_f32 v[148:149], v[172:173], v[236:237], v[148:149] op_sel:[0,1,0]
	ds_read2st64_b32 v[236:237], v231 offset0:96 offset1:100
	s_waitcnt lgkmcnt(4)
	v_pk_fma_f32 v[124:125], v[86:87], v[238:239], v[124:125] op_sel_hi:[1,0,1]
	v_pk_fma_f32 v[126:127], v[88:89], v[238:239], v[126:127] op_sel_hi:[1,0,1]
	v_pk_fma_f32 v[128:129], v[90:91], v[238:239], v[128:129] op_sel_hi:[1,0,1]
	v_pk_fma_f32 v[130:131], v[92:93], v[238:239], v[130:131] op_sel_hi:[1,0,1]
	v_pk_fma_f32 v[132:133], v[94:95], v[238:239], v[132:133] op_sel_hi:[1,0,1]
	v_pk_fma_f32 v[134:135], v[96:97], v[238:239], v[134:135] op_sel_hi:[1,0,1]
	v_pk_fma_f32 v[136:137], v[98:99], v[238:239], v[136:137] op_sel_hi:[1,0,1]
	v_pk_fma_f32 v[148:149], v[100:101], v[238:239], v[148:149] op_sel_hi:[1,0,1]
	v_fmac_f32_e32 v150, v1, v238
	v_pk_fma_f32 v[124:125], v[204:205], v[238:239], v[124:125] op_sel:[0,1,0]
	v_pk_fma_f32 v[126:127], v[206:207], v[238:239], v[126:127] op_sel:[0,1,0]
	v_pk_fma_f32 v[128:129], v[208:209], v[238:239], v[128:129] op_sel:[0,1,0]
	v_pk_fma_f32 v[130:131], v[210:211], v[238:239], v[130:131] op_sel:[0,1,0]
	v_pk_fma_f32 v[132:133], v[212:213], v[238:239], v[132:133] op_sel:[0,1,0]
	v_pk_fma_f32 v[134:135], v[166:167], v[238:239], v[134:135] op_sel:[0,1,0]
	v_pk_fma_f32 v[136:137], v[168:169], v[238:239], v[136:137] op_sel:[0,1,0]
	v_pk_fma_f32 v[148:149], v[170:171], v[238:239], v[148:149] op_sel:[0,1,0]
	v_pk_fma_f32 v[150:151], v[172:173], v[238:239], v[150:151] op_sel:[0,1,0]
	ds_read2st64_b32 v[238:239], v231 offset0:104 offset1:108
	s_waitcnt lgkmcnt(4)
	v_pk_fma_f32 v[124:125], v[84:85], v[240:241], v[124:125] op_sel_hi:[1,0,1]
	v_pk_fma_f32 v[126:127], v[86:87], v[240:241], v[126:127] op_sel_hi:[1,0,1]
	v_pk_fma_f32 v[128:129], v[88:89], v[240:241], v[128:129] op_sel_hi:[1,0,1]
	v_pk_fma_f32 v[130:131], v[90:91], v[240:241], v[130:131] op_sel_hi:[1,0,1]
	v_pk_fma_f32 v[132:133], v[92:93], v[240:241], v[132:133] op_sel_hi:[1,0,1]
	v_pk_fma_f32 v[134:135], v[94:95], v[240:241], v[134:135] op_sel_hi:[1,0,1]
	v_pk_fma_f32 v[136:137], v[96:97], v[240:241], v[136:137] op_sel_hi:[1,0,1]
	v_pk_fma_f32 v[148:149], v[98:99], v[240:241], v[148:149] op_sel_hi:[1,0,1]
	v_pk_fma_f32 v[150:151], v[100:101], v[240:241], v[150:151] op_sel_hi:[1,0,1]
	v_fmac_f32_e32 v152, v1, v240
	v_pk_fma_f32 v[124:125], v[202:203], v[240:241], v[124:125] op_sel:[0,1,0]
	v_pk_fma_f32 v[126:127], v[204:205], v[240:241], v[126:127] op_sel:[0,1,0]
	v_pk_fma_f32 v[128:129], v[206:207], v[240:241], v[128:129] op_sel:[0,1,0]
	v_pk_fma_f32 v[130:131], v[208:209], v[240:241], v[130:131] op_sel:[0,1,0]
	v_pk_fma_f32 v[132:133], v[210:211], v[240:241], v[132:133] op_sel:[0,1,0]
	v_pk_fma_f32 v[134:135], v[212:213], v[240:241], v[134:135] op_sel:[0,1,0]
	v_pk_fma_f32 v[136:137], v[166:167], v[240:241], v[136:137] op_sel:[0,1,0]
	v_pk_fma_f32 v[148:149], v[168:169], v[240:241], v[148:149] op_sel:[0,1,0]
	v_pk_fma_f32 v[150:151], v[170:171], v[240:241], v[150:151] op_sel:[0,1,0]
	v_pk_fma_f32 v[152:153], v[172:173], v[240:241], v[152:153] op_sel:[0,1,0]
	ds_read2st64_b32 v[240:241], v231 offset0:112 offset1:116
	s_waitcnt lgkmcnt(4)
; #define LAS __attribute__((address_space(3)))
;     static __device__ __forceinline__ void run(float (&acc)[32], const float (&wv)[31], const LAS float* U, int rb, int cch) {
;         const float uv = U[ring94(ring94(rb + S)) * 256 + cch];
; #pragma unroll
;         for (int o = 0; o < 32; ++o) { constexpr int dummy = 0; const int kk = S - o + dummy; if (kk >= 0 && kk <= 30) acc[o] += wv[kk] * uv; }
	v_pk_fma_f32 v[124:125], v[82:83], v[232:233], v[124:125] op_sel_hi:[1,0,1]
	v_pk_fma_f32 v[126:127], v[84:85], v[232:233], v[126:127] op_sel_hi:[1,0,1]
	v_pk_fma_f32 v[128:129], v[86:87], v[232:233], v[128:129] op_sel_hi:[1,0,1]
	v_pk_fma_f32 v[130:131], v[88:89], v[232:233], v[130:131] op_sel_hi:[1,0,1]
	v_pk_fma_f32 v[132:133], v[90:91], v[232:233], v[132:133] op_sel_hi:[1,0,1]
	v_pk_fma_f32 v[134:135], v[92:93], v[232:233], v[134:135] op_sel_hi:[1,0,1]
	v_pk_fma_f32 v[136:137], v[94:95], v[232:233], v[136:137] op_sel_hi:[1,0,1]
	v_pk_fma_f32 v[148:149], v[96:97], v[232:233], v[148:149] op_sel_hi:[1,0,1]
	v_pk_fma_f32 v[150:151], v[98:99], v[232:233], v[150:151] op_sel_hi:[1,0,1]
	v_pk_fma_f32 v[152:153], v[100:101], v[232:233], v[152:153] op_sel_hi:[1,0,1]
	v_fmac_f32_e32 v154, v1, v232
	v_pk_fma_f32 v[124:125], v[200:201], v[232:233], v[124:125] op_sel:[0,1,0]
	v_pk_fma_f32 v[126:127], v[202:203], v[232:233], v[126:127] op_sel:[0,1,0]
	v_pk_fma_f32 v[128:129], v[204:205], v[232:233], v[128:129] op_sel:[0,1,0]
	v_pk_fma_f32 v[130:131], v[206:207], v[232:233], v[130:131] op_sel:[0,1,0]
	v_pk_fma_f32 v[132:133], v[208:209], v[232:233], v[132:133] op_sel:[0,1,0]
	v_pk_fma_f32 v[134:135], v[210:211], v[232:233], v[134:135] op_sel:[0,1,0]
	v_pk_fma_f32 v[136:137], v[212:213], v[232:233], v[136:137] op_sel:[0,1,0]
	v_pk_fma_f32 v[148:149], v[166:167], v[232:233], v[148:149] op_sel:[0,1,0]
	v_pk_fma_f32 v[150:151], v[168:169], v[232:233], v[150:151] op_sel:[0,1,0]
	v_pk_fma_f32 v[152:153], v[170:171], v[232:233], v[152:153] op_sel:[0,1,0]
	v_pk_fma_f32 v[154:155], v[172:173], v[232:233], v[154:155] op_sel:[0,1,0]
	ds_read2st64_b32 v[232:233], v231 offset0:120 offset1:124
	s_waitcnt lgkmcnt(4)
	v_pk_fma_f32 v[124:125], v[80:81], v[234:235], v[124:125] op_sel_hi:[1,0,1]
	v_pk_fma_f32 v[126:127], v[82:83], v[234:235], v[126:127] op_sel_hi:[1,0,1]
	v_pk_fma_f32 v[128:129], v[84:85], v[234:235], v[128:129] op_sel_hi:[1,0,1]
	v_pk_fma_f32 v[130:131], v[86:87], v[234:235], v[130:131] op_sel_hi:[1,0,1]
	v_pk_fma_f32 v[132:133], v[88:89], v[234:235], v[132:133] op_sel_hi:[1,0,1]
	v_pk_fma_f32 v[134:135], v[90:91], v[234:235], v[134:135] op_sel_hi:[1,0,1]
	v_pk_fma_f32 v[136:137], v[92:93], v[234:235], v[136:137] op_sel_hi:[1,0,1]
	v_pk_fma_f32 v[148:149], v[94:95], v[234:235], v[148:149] op_sel_hi:[1,0,1]
	v_pk_fma_f32 v[150:151], v[96:97], v[234:235], v[150:151] op_sel_hi:[1,0,1]
	v_pk_fma_f32 v[152:153], v[98:99], v[234:235], v[152:153] op_sel_hi:[1,0,1]
	v_pk_fma_f32 v[154:155], v[100:101], v[234:235], v[154:155] op_sel_hi:[1,0,1]
	v_fmac_f32_e32 v156, v1, v234
	v_pk_fma_f32 v[124:125], v[198:199], v[234:235], v[124:125] op_sel:[0,1,0]
	v_pk_fma_f32 v[126:127], v[200:201], v[234:235], v[126:127] op_sel:[0,1,0]
	v_pk_fma_f32 v[128:129], v[202:203], v[234:235], v[128:129] op_sel:[0,1,0]
	v_pk_fma_f32 v[130:131], v[204:205], v[234:235], v[130:131] op_sel:[0,1,0]
	v_pk_fma_f32 v[132:133], v[206:207], v[234:235], v[132:133] op_sel:[0,1,0]
	v_pk_fma_f32 v[134:135], v[208:209], v[234:235], v[134:135] op_sel:[0,1,0]
	v_pk_fma_f32 v[136:137], v[210:211], v[234:235], v[136:137] op_sel:[0,1,0]
	v_pk_fma_f32 v[148:149], v[212:213], v[234:235], v[148:149] op_sel:[0,1,0]
	v_pk_fma_f32 v[150:151], v[166:167], v[234:235], v[150:151] op_sel:[0,1,0]
	v_pk_fma_f32 v[152:153], v[168:169], v[234:235], v[152:153] op_sel:[0,1,0]
	v_pk_fma_f32 v[154:155], v[170:171], v[234:235], v[154:155] op_sel:[0,1,0]
	v_pk_fma_f32 v[156:157], v[172:173], v[234:235], v[156:157] op_sel:[0,1,0]
	ds_read2st64_b32 v[234:235], v231 offset0:128 offset1:132
	s_waitcnt lgkmcnt(4)
	v_pk_fma_f32 v[124:125], v[78:79], v[236:237], v[124:125] op_sel_hi:[1,0,1]
	v_pk_fma_f32 v[126:127], v[80:81], v[236:237], v[126:127] op_sel_hi:[1,0,1]
	v_pk_fma_f32 v[128:129], v[82:83], v[236:237], v[128:129] op_sel_hi:[1,0,1]
	v_pk_fma_f32 v[130:131], v[84:85], v[236:237], v[130:131] op_sel_hi:[1,0,1]
	v_pk_fma_f32 v[132:133], v[86:87], v[236:237], v[132:133] op_sel_hi:[1,0,1]
	v_pk_fma_f32 v[134:135], v[88:89], v[236:237], v[134:135] op_sel_hi:[1,0,1]
	v_pk_fma_f32 v[136:137], v[90:91], v[236:237], v[136:137] op_sel_hi:[1,0,1]
	v_pk_fma_f32 v[148:149], v[92:93], v[236:237], v[148:149] op_sel_hi:[1,0,1]
	v_pk_fma_f32 v[150:151], v[94:95], v[236:237], v[150:151] op_sel_hi:[1,0,1]
	v_pk_fma_f32 v[152:153], v[96:97], v[236:237], v[152:153] op_sel_hi:[1,0,1]
	v_pk_fma_f32 v[154:155], v[98:99], v[236:237], v[154:155] op_sel_hi:[1,0,1]
	v_pk_fma_f32 v[156:157], v[100:101], v[236:237], v[156:157] op_sel_hi:[1,0,1]
	v_fmac_f32_e32 v158, v1, v236
	v_pk_fma_f32 v[124:125], v[196:197], v[236:237], v[124:125] op_sel:[0,1,0]
	v_pk_fma_f32 v[126:127], v[198:199], v[236:237], v[126:127] op_sel:[0,1,0]
	v_pk_fma_f32 v[128:129], v[200:201], v[236:237], v[128:129] op_sel:[0,1,0]
	v_pk_fma_f32 v[130:131], v[202:203], v[236:237], v[130:131] op_sel:[0,1,0]
	v_pk_fma_f32 v[132:133], v[204:205], v[236:237], v[132:133] op_sel:[0,1,0]
	v_pk_fma_f32 v[134:135], v[206:207], v[236:237], v[134:135] op_sel:[0,1,0]
	v_pk_fma_f32 v[136:137], v[208:209], v[236:237], v[136:137] op_sel:[0,1,0]
	v_pk_fma_f32 v[148:149], v[210:211], v[236:237], v[148:149] op_sel:[0,1,0]
	v_pk_fma_f32 v[150:151], v[212:213], v[236:237], v[150:151] op_sel:[0,1,0]
	v_pk_fma_f32 v[152:153], v[166:167], v[236:237], v[152:153] op_sel:[0,1,0]
	v_pk_fma_f32 v[154:155], v[168:169], v[236:237], v[154:155] op_sel:[0,1,0]
	v_pk_fma_f32 v[156:157], v[170:171], v[236:237], v[156:157] op_sel:[0,1,0]
	v_pk_fma_f32 v[158:159], v[172:173], v[236:237], v[158:159] op_sel:[0,1,0]
	ds_read2st64_b32 v[236:237], v231 offset0:136 offset1:140
	s_waitcnt lgkmcnt(4)
; #define LAS __attribute__((address_space(3)))
;     static __device__ __forceinline__ void run(float (&acc)[32], const float (&wv)[31], const LAS float* U, int rb, int cch) {
;         const float uv = U[ring94(ring94(rb + S)) * 256 + cch];
; #pragma unroll
;         for (int o = 0; o < 32; ++o) { constexpr int dummy = 0; const int kk = S - o + dummy; if (kk >= 0 && kk <= 30) acc[o] += wv[kk] * uv; }
	v_pk_fma_f32 v[124:125], v[76:77], v[238:239], v[124:125] op_sel_hi:[1,0,1]
	v_pk_fma_f32 v[126:127], v[78:79], v[238:239], v[126:127] op_sel_hi:[1,0,1]
	v_pk_fma_f32 v[128:129], v[80:81], v[238:239], v[128:129] op_sel_hi:[1,0,1]
	v_pk_fma_f32 v[130:131], v[82:83], v[238:239], v[130:131] op_sel_hi:[1,0,1]
	v_pk_fma_f32 v[132:133], v[84:85], v[238:239], v[132:133] op_sel_hi:[1,0,1]
	v_pk_fma_f32 v[134:135], v[86:87], v[238:239], v[134:135] op_sel_hi:[1,0,1]
	v_pk_fma_f32 v[136:137], v[88:89], v[238:239], v[136:137] op_sel_hi:[1,0,1]
	v_pk_fma_f32 v[148:149], v[90:91], v[238:239], v[148:149] op_sel_hi:[1,0,1]
	v_pk_fma_f32 v[150:151], v[92:93], v[238:239], v[150:151] op_sel_hi:[1,0,1]
	v_pk_fma_f32 v[152:153], v[94:95], v[238:239], v[152:153] op_sel_hi:[1,0,1]
	v_pk_fma_f32 v[154:155], v[96:97], v[238:239], v[154:155] op_sel_hi:[1,0,1]
	v_pk_fma_f32 v[156:157], v[98:99], v[238:239], v[156:157] op_sel_hi:[1,0,1]
	v_pk_fma_f32 v[158:159], v[100:101], v[238:239], v[158:159] op_sel_hi:[1,0,1]
	v_fmac_f32_e32 v160, v1, v238
	v_pk_fma_f32 v[124:125], v[194:195], v[238:239], v[124:125] op_sel:[0,1,0]
	v_pk_fma_f32 v[126:127], v[196:197], v[238:239], v[126:127] op_sel:[0,1,0]
	v_pk_fma_f32 v[128:129], v[198:199], v[238:239], v[128:129] op_sel:[0,1,0]
	v_pk_fma_f32 v[130:131], v[200:201], v[238:239], v[130:131] op_sel:[0,1,0]
	v_pk_fma_f32 v[132:133], v[202:203], v[238:239], v[132:133] op_sel:[0,1,0]
	v_pk_fma_f32 v[134:135], v[204:205], v[238:239], v[134:135] op_sel:[0,1,0]
	v_pk_fma_f32 v[136:137], v[206:207], v[238:239], v[136:137] op_sel:[0,1,0]
	v_pk_fma_f32 v[148:149], v[208:209], v[238:239], v[148:149] op_sel:[0,1,0]
	v_pk_fma_f32 v[150:151], v[210:211], v[238:239], v[150:151] op_sel:[0,1,0]
	v_pk_fma_f32 v[152:153], v[212:213], v[238:239], v[152:153] op_sel:[0,1,0]
	v_pk_fma_f32 v[154:155], v[166:167], v[238:239], v[154:155] op_sel:[0,1,0]
	v_pk_fma_f32 v[156:157], v[168:169], v[238:239], v[156:157] op_sel:[0,1,0]
	v_pk_fma_f32 v[158:159], v[170:171], v[238:239], v[158:159] op_sel:[0,1,0]
	v_pk_fma_f32 v[160:161], v[172:173], v[238:239], v[160:161] op_sel:[0,1,0]
	ds_read2st64_b32 v[238:239], v231 offset0:144 offset1:148
	s_waitcnt lgkmcnt(4)
	v_pk_fma_f32 v[124:125], v[74:75], v[240:241], v[124:125] op_sel_hi:[1,0,1]
	v_pk_fma_f32 v[126:127], v[76:77], v[240:241], v[126:127] op_sel_hi:[1,0,1]
	v_pk_fma_f32 v[128:129], v[78:79], v[240:241], v[128:129] op_sel_hi:[1,0,1]
	v_pk_fma_f32 v[130:131], v[80:81], v[240:241], v[130:131] op_sel_hi:[1,0,1]
	v_pk_fma_f32 v[132:133], v[82:83], v[240:241], v[132:133] op_sel_hi:[1,0,1]
	v_pk_fma_f32 v[134:135], v[84:85], v[240:241], v[134:135] op_sel_hi:[1,0,1]
	v_pk_fma_f32 v[136:137], v[86:87], v[240:241], v[136:137] op_sel_hi:[1,0,1]
	v_pk_fma_f32 v[148:149], v[88:89], v[240:241], v[148:149] op_sel_hi:[1,0,1]
	v_pk_fma_f32 v[150:151], v[90:91], v[240:241], v[150:151] op_sel_hi:[1,0,1]
	v_pk_fma_f32 v[152:153], v[92:93], v[240:241], v[152:153] op_sel_hi:[1,0,1]
	v_pk_fma_f32 v[154:155], v[94:95], v[240:241], v[154:155] op_sel_hi:[1,0,1]
	v_pk_fma_f32 v[156:157], v[96:97], v[240:241], v[156:157] op_sel_hi:[1,0,1]
	v_pk_fma_f32 v[158:159], v[98:99], v[240:241], v[158:159] op_sel_hi:[1,0,1]
	v_pk_fma_f32 v[160:161], v[100:101], v[240:241], v[160:161] op_sel_hi:[1,0,1]
	v_fmac_f32_e32 v162, v1, v240
	v_pk_fma_f32 v[124:125], v[192:193], v[240:241], v[124:125] op_sel:[0,1,0]
	v_pk_fma_f32 v[126:127], v[194:195], v[240:241], v[126:127] op_sel:[0,1,0]
	v_pk_fma_f32 v[128:129], v[196:197], v[240:241], v[128:129] op_sel:[0,1,0]
	v_pk_fma_f32 v[130:131], v[198:199], v[240:241], v[130:131] op_sel:[0,1,0]
	v_pk_fma_f32 v[132:133], v[200:201], v[240:241], v[132:133] op_sel:[0,1,0]
	v_pk_fma_f32 v[134:135], v[202:203], v[240:241], v[134:135] op_sel:[0,1,0]
	v_pk_fma_f32 v[136:137], v[204:205], v[240:241], v[136:137] op_sel:[0,1,0]
	v_pk_fma_f32 v[148:149], v[206:207], v[240:241], v[148:149] op_sel:[0,1,0]
	v_pk_fma_f32 v[150:151], v[208:209], v[240:241], v[150:151] op_sel:[0,1,0]
	v_pk_fma_f32 v[152:153], v[210:211], v[240:241], v[152:153] op_sel:[0,1,0]
	v_pk_fma_f32 v[154:155], v[212:213], v[240:241], v[154:155] op_sel:[0,1,0]
	v_pk_fma_f32 v[156:157], v[166:167], v[240:241], v[156:157] op_sel:[0,1,0]
	v_pk_fma_f32 v[158:159], v[168:169], v[240:241], v[158:159] op_sel:[0,1,0]
	v_pk_fma_f32 v[160:161], v[170:171], v[240:241], v[160:161] op_sel:[0,1,0]
	v_pk_fma_f32 v[162:163], v[172:173], v[240:241], v[162:163] op_sel:[0,1,0]
	ds_read2st64_b32 v[240:241], v231 offset0:152 offset1:156
	s_waitcnt lgkmcnt(4)
; #define LAS __attribute__((address_space(3)))
;     static __device__ __forceinline__ void run(float (&acc)[32], const float (&wv)[31], const LAS float* U, int rb, int cch) {
;         const float uv = U[ring94(ring94(rb + S)) * 256 + cch];
; #pragma unroll
;         for (int o = 0; o < 32; ++o) { constexpr int dummy = 0; const int kk = S - o + dummy; if (kk >= 0 && kk <= 30) acc[o] += wv[kk] * uv; }
	v_pk_fma_f32 v[124:125], v[72:73], v[232:233], v[124:125] op_sel_hi:[1,0,1]
	v_pk_fma_f32 v[126:127], v[74:75], v[232:233], v[126:127] op_sel_hi:[1,0,1]
	v_pk_fma_f32 v[128:129], v[76:77], v[232:233], v[128:129] op_sel_hi:[1,0,1]
	v_pk_fma_f32 v[130:131], v[78:79], v[232:233], v[130:131] op_sel_hi:[1,0,1]
	v_pk_fma_f32 v[132:133], v[80:81], v[232:233], v[132:133] op_sel_hi:[1,0,1]
	v_pk_fma_f32 v[134:135], v[82:83], v[232:233], v[134:135] op_sel_hi:[1,0,1]
	v_pk_fma_f32 v[136:137], v[84:85], v[232:233], v[136:137] op_sel_hi:[1,0,1]
	v_pk_fma_f32 v[148:149], v[86:87], v[232:233], v[148:149] op_sel_hi:[1,0,1]
	v_pk_fma_f32 v[150:151], v[88:89], v[232:233], v[150:151] op_sel_hi:[1,0,1]
	v_pk_fma_f32 v[152:153], v[90:91], v[232:233], v[152:153] op_sel_hi:[1,0,1]
	v_pk_fma_f32 v[154:155], v[92:93], v[232:233], v[154:155] op_sel_hi:[1,0,1]
	v_pk_fma_f32 v[156:157], v[94:95], v[232:233], v[156:157] op_sel_hi:[1,0,1]
	v_pk_fma_f32 v[158:159], v[96:97], v[232:233], v[158:159] op_sel_hi:[1,0,1]
	v_pk_fma_f32 v[160:161], v[98:99], v[232:233], v[160:161] op_sel_hi:[1,0,1]
	v_pk_fma_f32 v[162:163], v[100:101], v[232:233], v[162:163] op_sel_hi:[1,0,1]
	v_fmac_f32_e32 v164, v1, v232
	v_fmac_f32_e32 v125, v72, v233
	v_pk_fma_f32 v[126:127], v[192:193], v[232:233], v[126:127] op_sel:[0,1,0]
	v_pk_fma_f32 v[128:129], v[194:195], v[232:233], v[128:129] op_sel:[0,1,0]
	v_pk_fma_f32 v[130:131], v[196:197], v[232:233], v[130:131] op_sel:[0,1,0]
	v_pk_fma_f32 v[132:133], v[198:199], v[232:233], v[132:133] op_sel:[0,1,0]
	v_pk_fma_f32 v[134:135], v[200:201], v[232:233], v[134:135] op_sel:[0,1,0]
	v_pk_fma_f32 v[136:137], v[202:203], v[232:233], v[136:137] op_sel:[0,1,0]
	v_pk_fma_f32 v[148:149], v[204:205], v[232:233], v[148:149] op_sel:[0,1,0]
	v_pk_fma_f32 v[150:151], v[206:207], v[232:233], v[150:151] op_sel:[0,1,0]
	v_pk_fma_f32 v[152:153], v[208:209], v[232:233], v[152:153] op_sel:[0,1,0]
	v_pk_fma_f32 v[154:155], v[210:211], v[232:233], v[154:155] op_sel:[0,1,0]
	v_pk_fma_f32 v[156:157], v[212:213], v[232:233], v[156:157] op_sel:[0,1,0]
	v_pk_fma_f32 v[158:159], v[166:167], v[232:233], v[158:159] op_sel:[0,1,0]
	v_pk_fma_f32 v[160:161], v[168:169], v[232:233], v[160:161] op_sel:[0,1,0]
	v_pk_fma_f32 v[162:163], v[170:171], v[232:233], v[162:163] op_sel:[0,1,0]
	v_pk_fma_f32 v[164:165], v[172:173], v[232:233], v[164:165] op_sel:[0,1,0]
	ds_read2st64_b32 v[232:233], v231 offset0:160 offset1:164
	s_waitcnt lgkmcnt(4)
	v_pk_fma_f32 v[126:127], v[72:73], v[234:235], v[126:127] op_sel_hi:[1,0,1]
	v_pk_fma_f32 v[128:129], v[74:75], v[234:235], v[128:129] op_sel_hi:[1,0,1]
	v_pk_fma_f32 v[130:131], v[76:77], v[234:235], v[130:131] op_sel_hi:[1,0,1]
	v_pk_fma_f32 v[132:133], v[78:79], v[234:235], v[132:133] op_sel_hi:[1,0,1]
	v_pk_fma_f32 v[134:135], v[80:81], v[234:235], v[134:135] op_sel_hi:[1,0,1]
	v_pk_fma_f32 v[136:137], v[82:83], v[234:235], v[136:137] op_sel_hi:[1,0,1]
	v_pk_fma_f32 v[148:149], v[84:85], v[234:235], v[148:149] op_sel_hi:[1,0,1]
	v_pk_fma_f32 v[150:151], v[86:87], v[234:235], v[150:151] op_sel_hi:[1,0,1]
	v_pk_fma_f32 v[152:153], v[88:89], v[234:235], v[152:153] op_sel_hi:[1,0,1]
	v_pk_fma_f32 v[154:155], v[90:91], v[234:235], v[154:155] op_sel_hi:[1,0,1]
	v_pk_fma_f32 v[156:157], v[92:93], v[234:235], v[156:157] op_sel_hi:[1,0,1]
	v_pk_fma_f32 v[158:159], v[94:95], v[234:235], v[158:159] op_sel_hi:[1,0,1]
	v_pk_fma_f32 v[160:161], v[96:97], v[234:235], v[160:161] op_sel_hi:[1,0,1]
	v_pk_fma_f32 v[162:163], v[98:99], v[234:235], v[162:163] op_sel_hi:[1,0,1]
	v_pk_fma_f32 v[164:165], v[100:101], v[234:235], v[164:165] op_sel_hi:[1,0,1]
	v_fmac_f32_e32 v127, v72, v235
	v_pk_fma_f32 v[128:129], v[192:193], v[234:235], v[128:129] op_sel:[0,1,0]
	v_pk_fma_f32 v[130:131], v[194:195], v[234:235], v[130:131] op_sel:[0,1,0]
	v_pk_fma_f32 v[132:133], v[196:197], v[234:235], v[132:133] op_sel:[0,1,0]
	v_pk_fma_f32 v[134:135], v[198:199], v[234:235], v[134:135] op_sel:[0,1,0]
	v_pk_fma_f32 v[136:137], v[200:201], v[234:235], v[136:137] op_sel:[0,1,0]
	v_pk_fma_f32 v[148:149], v[202:203], v[234:235], v[148:149] op_sel:[0,1,0]
	v_pk_fma_f32 v[150:151], v[204:205], v[234:235], v[150:151] op_sel:[0,1,0]
	v_pk_fma_f32 v[152:153], v[206:207], v[234:235], v[152:153] op_sel:[0,1,0]
	v_pk_fma_f32 v[154:155], v[208:209], v[234:235], v[154:155] op_sel:[0,1,0]
	v_pk_fma_f32 v[156:157], v[210:211], v[234:235], v[156:157] op_sel:[0,1,0]
	v_pk_fma_f32 v[158:159], v[212:213], v[234:235], v[158:159] op_sel:[0,1,0]
	v_pk_fma_f32 v[160:161], v[166:167], v[234:235], v[160:161] op_sel:[0,1,0]
	v_pk_fma_f32 v[162:163], v[168:169], v[234:235], v[162:163] op_sel:[0,1,0]
	v_pk_fma_f32 v[164:165], v[170:171], v[234:235], v[164:165] op_sel:[0,1,0]
	ds_read2st64_b32 v[234:235], v231 offset0:168 offset1:172
	s_waitcnt lgkmcnt(4)
; #define LAS __attribute__((address_space(3)))
;     static __device__ __forceinline__ void run(float (&acc)[32], const float (&wv)[31], const LAS float* U, int rb, int cch) {
;         const float uv = U[ring94(ring94(rb + S)) * 256 + cch];
; #pragma unroll
;         for (int o = 0; o < 32; ++o) { constexpr int dummy = 0; const int kk = S - o + dummy; if (kk >= 0 && kk <= 30) acc[o] += wv[kk] * uv; }
	v_pk_fma_f32 v[128:129], v[72:73], v[236:237], v[128:129] op_sel_hi:[1,0,1]
	v_pk_fma_f32 v[130:131], v[74:75], v[236:237], v[130:131] op_sel_hi:[1,0,1]
	v_pk_fma_f32 v[132:133], v[76:77], v[236:237], v[132:133] op_sel_hi:[1,0,1]
	v_pk_fma_f32 v[134:135], v[78:79], v[236:237], v[134:135] op_sel_hi:[1,0,1]
	v_pk_fma_f32 v[136:137], v[80:81], v[236:237], v[136:137] op_sel_hi:[1,0,1]
	v_pk_fma_f32 v[148:149], v[82:83], v[236:237], v[148:149] op_sel_hi:[1,0,1]
	v_pk_fma_f32 v[150:151], v[84:85], v[236:237], v[150:151] op_sel_hi:[1,0,1]
	v_pk_fma_f32 v[152:153], v[86:87], v[236:237], v[152:153] op_sel_hi:[1,0,1]
	v_pk_fma_f32 v[154:155], v[88:89], v[236:237], v[154:155] op_sel_hi:[1,0,1]
	v_pk_fma_f32 v[156:157], v[90:91], v[236:237], v[156:157] op_sel_hi:[1,0,1]
	v_pk_fma_f32 v[158:159], v[92:93], v[236:237], v[158:159] op_sel_hi:[1,0,1]
	v_pk_fma_f32 v[160:161], v[94:95], v[236:237], v[160:161] op_sel_hi:[1,0,1]
	v_pk_fma_f32 v[162:163], v[96:97], v[236:237], v[162:163] op_sel_hi:[1,0,1]
	v_pk_fma_f32 v[164:165], v[98:99], v[236:237], v[164:165] op_sel_hi:[1,0,1]
	v_fmac_f32_e32 v129, v72, v237
	v_pk_fma_f32 v[130:131], v[192:193], v[236:237], v[130:131] op_sel:[0,1,0]
	v_pk_fma_f32 v[132:133], v[194:195], v[236:237], v[132:133] op_sel:[0,1,0]
	v_pk_fma_f32 v[134:135], v[196:197], v[236:237], v[134:135] op_sel:[0,1,0]
	v_pk_fma_f32 v[136:137], v[198:199], v[236:237], v[136:137] op_sel:[0,1,0]
	v_pk_fma_f32 v[148:149], v[200:201], v[236:237], v[148:149] op_sel:[0,1,0]
	v_pk_fma_f32 v[150:151], v[202:203], v[236:237], v[150:151] op_sel:[0,1,0]
	v_pk_fma_f32 v[152:153], v[204:205], v[236:237], v[152:153] op_sel:[0,1,0]
	v_pk_fma_f32 v[154:155], v[206:207], v[236:237], v[154:155] op_sel:[0,1,0]
	v_pk_fma_f32 v[156:157], v[208:209], v[236:237], v[156:157] op_sel:[0,1,0]
	v_pk_fma_f32 v[158:159], v[210:211], v[236:237], v[158:159] op_sel:[0,1,0]
	v_pk_fma_f32 v[160:161], v[212:213], v[236:237], v[160:161] op_sel:[0,1,0]
	v_pk_fma_f32 v[162:163], v[166:167], v[236:237], v[162:163] op_sel:[0,1,0]
	v_pk_fma_f32 v[164:165], v[168:169], v[236:237], v[164:165] op_sel:[0,1,0]
	ds_read2st64_b32 v[236:237], v231 offset0:176 offset1:180
	s_waitcnt lgkmcnt(4)
	v_pk_fma_f32 v[130:131], v[72:73], v[238:239], v[130:131] op_sel_hi:[1,0,1]
	v_pk_fma_f32 v[132:133], v[74:75], v[238:239], v[132:133] op_sel_hi:[1,0,1]
	v_pk_fma_f32 v[134:135], v[76:77], v[238:239], v[134:135] op_sel_hi:[1,0,1]
	v_pk_fma_f32 v[136:137], v[78:79], v[238:239], v[136:137] op_sel_hi:[1,0,1]
	v_pk_fma_f32 v[148:149], v[80:81], v[238:239], v[148:149] op_sel_hi:[1,0,1]
	v_pk_fma_f32 v[150:151], v[82:83], v[238:239], v[150:151] op_sel_hi:[1,0,1]
	v_pk_fma_f32 v[152:153], v[84:85], v[238:239], v[152:153] op_sel_hi:[1,0,1]
	v_pk_fma_f32 v[154:155], v[86:87], v[238:239], v[154:155] op_sel_hi:[1,0,1]
	v_pk_fma_f32 v[156:157], v[88:89], v[238:239], v[156:157] op_sel_hi:[1,0,1]
	v_pk_fma_f32 v[158:159], v[90:91], v[238:239], v[158:159] op_sel_hi:[1,0,1]
	v_pk_fma_f32 v[160:161], v[92:93], v[238:239], v[160:161] op_sel_hi:[1,0,1]
	v_pk_fma_f32 v[162:163], v[94:95], v[238:239], v[162:163] op_sel_hi:[1,0,1]
	v_pk_fma_f32 v[164:165], v[96:97], v[238:239], v[164:165] op_sel_hi:[1,0,1]
	v_fmac_f32_e32 v131, v72, v239
	v_pk_fma_f32 v[132:133], v[192:193], v[238:239], v[132:133] op_sel:[0,1,0]
	v_pk_fma_f32 v[134:135], v[194:195], v[238:239], v[134:135] op_sel:[0,1,0]
	v_pk_fma_f32 v[136:137], v[196:197], v[238:239], v[136:137] op_sel:[0,1,0]
	v_pk_fma_f32 v[148:149], v[198:199], v[238:239], v[148:149] op_sel:[0,1,0]
	v_pk_fma_f32 v[150:151], v[200:201], v[238:239], v[150:151] op_sel:[0,1,0]
	v_pk_fma_f32 v[152:153], v[202:203], v[238:239], v[152:153] op_sel:[0,1,0]
	v_pk_fma_f32 v[154:155], v[204:205], v[238:239], v[154:155] op_sel:[0,1,0]
	v_pk_fma_f32 v[156:157], v[206:207], v[238:239], v[156:157] op_sel:[0,1,0]
	v_pk_fma_f32 v[158:159], v[208:209], v[238:239], v[158:159] op_sel:[0,1,0]
	v_pk_fma_f32 v[160:161], v[210:211], v[238:239], v[160:161] op_sel:[0,1,0]
	v_pk_fma_f32 v[162:163], v[212:213], v[238:239], v[162:163] op_sel:[0,1,0]
	v_pk_fma_f32 v[164:165], v[166:167], v[238:239], v[164:165] op_sel:[0,1,0]
	ds_read2st64_b32 v[238:239], v231 offset0:184 offset1:188
	s_waitcnt lgkmcnt(4)
	v_pk_fma_f32 v[132:133], v[72:73], v[240:241], v[132:133] op_sel_hi:[1,0,1]
	v_pk_fma_f32 v[134:135], v[74:75], v[240:241], v[134:135] op_sel_hi:[1,0,1]
	v_pk_fma_f32 v[136:137], v[76:77], v[240:241], v[136:137] op_sel_hi:[1,0,1]
	v_pk_fma_f32 v[148:149], v[78:79], v[240:241], v[148:149] op_sel_hi:[1,0,1]
	v_pk_fma_f32 v[150:151], v[80:81], v[240:241], v[150:151] op_sel_hi:[1,0,1]
	v_pk_fma_f32 v[152:153], v[82:83], v[240:241], v[152:153] op_sel_hi:[1,0,1]
	v_pk_fma_f32 v[154:155], v[84:85], v[240:241], v[154:155] op_sel_hi:[1,0,1]
	v_pk_fma_f32 v[156:157], v[86:87], v[240:241], v[156:157] op_sel_hi:[1,0,1]
	v_pk_fma_f32 v[158:159], v[88:89], v[240:241], v[158:159] op_sel_hi:[1,0,1]
	v_pk_fma_f32 v[160:161], v[90:91], v[240:241], v[160:161] op_sel_hi:[1,0,1]
	v_pk_fma_f32 v[162:163], v[92:93], v[240:241], v[162:163] op_sel_hi:[1,0,1]
	v_pk_fma_f32 v[164:165], v[94:95], v[240:241], v[164:165] op_sel_hi:[1,0,1]
	v_fmac_f32_e32 v133, v72, v241
	v_pk_fma_f32 v[134:135], v[192:193], v[240:241], v[134:135] op_sel:[0,1,0]
	v_pk_fma_f32 v[136:137], v[194:195], v[240:241], v[136:137] op_sel:[0,1,0]
	v_pk_fma_f32 v[148:149], v[196:197], v[240:241], v[148:149] op_sel:[0,1,0]
	v_pk_fma_f32 v[150:151], v[198:199], v[240:241], v[150:151] op_sel:[0,1,0]
	v_pk_fma_f32 v[152:153], v[200:201], v[240:241], v[152:153] op_sel:[0,1,0]
	v_pk_fma_f32 v[154:155], v[202:203], v[240:241], v[154:155] op_sel:[0,1,0]
	v_pk_fma_f32 v[156:157], v[204:205], v[240:241], v[156:157] op_sel:[0,1,0]
	v_pk_fma_f32 v[158:159], v[206:207], v[240:241], v[158:159] op_sel:[0,1,0]
	v_pk_fma_f32 v[160:161], v[208:209], v[240:241], v[160:161] op_sel:[0,1,0]
	v_pk_fma_f32 v[162:163], v[210:211], v[240:241], v[162:163] op_sel:[0,1,0]
	v_pk_fma_f32 v[164:165], v[212:213], v[240:241], v[164:165] op_sel:[0,1,0]
	ds_read2st64_b32 v[240:241], v231 offset0:192 offset1:196
	s_waitcnt lgkmcnt(4)
; #define LAS __attribute__((address_space(3)))
;     static __device__ __forceinline__ void run(float (&acc)[32], const float (&wv)[31], const LAS float* U, int rb, int cch) {
;         const float uv = U[ring94(ring94(rb + S)) * 256 + cch];
; #pragma unroll
;         for (int o = 0; o < 32; ++o) { constexpr int dummy = 0; const int kk = S - o + dummy; if (kk >= 0 && kk <= 30) acc[o] += wv[kk] * uv; }
	v_pk_fma_f32 v[134:135], v[72:73], v[232:233], v[134:135] op_sel_hi:[1,0,1]
	v_pk_fma_f32 v[136:137], v[74:75], v[232:233], v[136:137] op_sel_hi:[1,0,1]
	v_pk_fma_f32 v[148:149], v[76:77], v[232:233], v[148:149] op_sel_hi:[1,0,1]
	v_pk_fma_f32 v[150:151], v[78:79], v[232:233], v[150:151] op_sel_hi:[1,0,1]
	v_pk_fma_f32 v[152:153], v[80:81], v[232:233], v[152:153] op_sel_hi:[1,0,1]
	v_pk_fma_f32 v[154:155], v[82:83], v[232:233], v[154:155] op_sel_hi:[1,0,1]
	v_pk_fma_f32 v[156:157], v[84:85], v[232:233], v[156:157] op_sel_hi:[1,0,1]
	v_pk_fma_f32 v[158:159], v[86:87], v[232:233], v[158:159] op_sel_hi:[1,0,1]
	v_pk_fma_f32 v[160:161], v[88:89], v[232:233], v[160:161] op_sel_hi:[1,0,1]
	v_pk_fma_f32 v[162:163], v[90:91], v[232:233], v[162:163] op_sel_hi:[1,0,1]
	v_pk_fma_f32 v[164:165], v[92:93], v[232:233], v[164:165] op_sel_hi:[1,0,1]
	v_fmac_f32_e32 v135, v72, v233
	v_pk_fma_f32 v[136:137], v[192:193], v[232:233], v[136:137] op_sel:[0,1,0]
	v_pk_fma_f32 v[148:149], v[194:195], v[232:233], v[148:149] op_sel:[0,1,0]
	v_pk_fma_f32 v[150:151], v[196:197], v[232:233], v[150:151] op_sel:[0,1,0]
	v_pk_fma_f32 v[152:153], v[198:199], v[232:233], v[152:153] op_sel:[0,1,0]
	v_pk_fma_f32 v[154:155], v[200:201], v[232:233], v[154:155] op_sel:[0,1,0]
	v_pk_fma_f32 v[156:157], v[202:203], v[232:233], v[156:157] op_sel:[0,1,0]
	v_pk_fma_f32 v[158:159], v[204:205], v[232:233], v[158:159] op_sel:[0,1,0]
	v_pk_fma_f32 v[160:161], v[206:207], v[232:233], v[160:161] op_sel:[0,1,0]
	v_pk_fma_f32 v[162:163], v[208:209], v[232:233], v[162:163] op_sel:[0,1,0]
	v_pk_fma_f32 v[164:165], v[210:211], v[232:233], v[164:165] op_sel:[0,1,0]
	ds_read2st64_b32 v[232:233], v231 offset0:200 offset1:204
	s_waitcnt lgkmcnt(4)
	v_pk_fma_f32 v[136:137], v[72:73], v[234:235], v[136:137] op_sel_hi:[1,0,1]
	v_pk_fma_f32 v[148:149], v[74:75], v[234:235], v[148:149] op_sel_hi:[1,0,1]
	v_pk_fma_f32 v[150:151], v[76:77], v[234:235], v[150:151] op_sel_hi:[1,0,1]
	v_pk_fma_f32 v[152:153], v[78:79], v[234:235], v[152:153] op_sel_hi:[1,0,1]
	v_pk_fma_f32 v[154:155], v[80:81], v[234:235], v[154:155] op_sel_hi:[1,0,1]
	v_pk_fma_f32 v[156:157], v[82:83], v[234:235], v[156:157] op_sel_hi:[1,0,1]
	v_pk_fma_f32 v[158:159], v[84:85], v[234:235], v[158:159] op_sel_hi:[1,0,1]
	v_pk_fma_f32 v[160:161], v[86:87], v[234:235], v[160:161] op_sel_hi:[1,0,1]
	v_pk_fma_f32 v[162:163], v[88:89], v[234:235], v[162:163] op_sel_hi:[1,0,1]
	v_pk_fma_f32 v[164:165], v[90:91], v[234:235], v[164:165] op_sel_hi:[1,0,1]
	v_fmac_f32_e32 v137, v72, v235
	v_pk_fma_f32 v[148:149], v[192:193], v[234:235], v[148:149] op_sel:[0,1,0]
	v_pk_fma_f32 v[150:151], v[194:195], v[234:235], v[150:151] op_sel:[0,1,0]
	v_pk_fma_f32 v[152:153], v[196:197], v[234:235], v[152:153] op_sel:[0,1,0]
	v_pk_fma_f32 v[154:155], v[198:199], v[234:235], v[154:155] op_sel:[0,1,0]
	v_pk_fma_f32 v[156:157], v[200:201], v[234:235], v[156:157] op_sel:[0,1,0]
	v_pk_fma_f32 v[158:159], v[202:203], v[234:235], v[158:159] op_sel:[0,1,0]
	v_pk_fma_f32 v[160:161], v[204:205], v[234:235], v[160:161] op_sel:[0,1,0]
	v_pk_fma_f32 v[162:163], v[206:207], v[234:235], v[162:163] op_sel:[0,1,0]
	v_pk_fma_f32 v[164:165], v[208:209], v[234:235], v[164:165] op_sel:[0,1,0]
	ds_read2st64_b32 v[234:235], v231 offset0:208 offset1:212
	s_waitcnt lgkmcnt(4)
	v_pk_fma_f32 v[148:149], v[72:73], v[236:237], v[148:149] op_sel_hi:[1,0,1]
	v_pk_fma_f32 v[150:151], v[74:75], v[236:237], v[150:151] op_sel_hi:[1,0,1]
	v_pk_fma_f32 v[152:153], v[76:77], v[236:237], v[152:153] op_sel_hi:[1,0,1]
	v_pk_fma_f32 v[154:155], v[78:79], v[236:237], v[154:155] op_sel_hi:[1,0,1]
	v_pk_fma_f32 v[156:157], v[80:81], v[236:237], v[156:157] op_sel_hi:[1,0,1]
	v_pk_fma_f32 v[158:159], v[82:83], v[236:237], v[158:159] op_sel_hi:[1,0,1]
	v_pk_fma_f32 v[160:161], v[84:85], v[236:237], v[160:161] op_sel_hi:[1,0,1]
	v_pk_fma_f32 v[162:163], v[86:87], v[236:237], v[162:163] op_sel_hi:[1,0,1]
	v_pk_fma_f32 v[164:165], v[88:89], v[236:237], v[164:165] op_sel_hi:[1,0,1]
	v_fmac_f32_e32 v149, v72, v237
	v_pk_fma_f32 v[150:151], v[192:193], v[236:237], v[150:151] op_sel:[0,1,0]
	v_pk_fma_f32 v[152:153], v[194:195], v[236:237], v[152:153] op_sel:[0,1,0]
	v_pk_fma_f32 v[154:155], v[196:197], v[236:237], v[154:155] op_sel:[0,1,0]
	v_pk_fma_f32 v[156:157], v[198:199], v[236:237], v[156:157] op_sel:[0,1,0]
	v_pk_fma_f32 v[158:159], v[200:201], v[236:237], v[158:159] op_sel:[0,1,0]
	v_pk_fma_f32 v[160:161], v[202:203], v[236:237], v[160:161] op_sel:[0,1,0]
	v_pk_fma_f32 v[162:163], v[204:205], v[236:237], v[162:163] op_sel:[0,1,0]
	v_pk_fma_f32 v[164:165], v[206:207], v[236:237], v[164:165] op_sel:[0,1,0]
	ds_read2st64_b32 v[236:237], v231 offset0:216 offset1:220
	s_waitcnt lgkmcnt(4)
	v_pk_fma_f32 v[150:151], v[72:73], v[238:239], v[150:151] op_sel_hi:[1,0,1]
	v_pk_fma_f32 v[152:153], v[74:75], v[238:239], v[152:153] op_sel_hi:[1,0,1]
	v_pk_fma_f32 v[154:155], v[76:77], v[238:239], v[154:155] op_sel_hi:[1,0,1]
	v_pk_fma_f32 v[156:157], v[78:79], v[238:239], v[156:157] op_sel_hi:[1,0,1]
	v_pk_fma_f32 v[158:159], v[80:81], v[238:239], v[158:159] op_sel_hi:[1,0,1]
	v_pk_fma_f32 v[160:161], v[82:83], v[238:239], v[160:161] op_sel_hi:[1,0,1]
	v_pk_fma_f32 v[162:163], v[84:85], v[238:239], v[162:163] op_sel_hi:[1,0,1]
	v_pk_fma_f32 v[164:165], v[86:87], v[238:239], v[164:165] op_sel_hi:[1,0,1]
	v_fmac_f32_e32 v151, v72, v239
	v_pk_fma_f32 v[152:153], v[192:193], v[238:239], v[152:153] op_sel:[0,1,0]
	v_pk_fma_f32 v[154:155], v[194:195], v[238:239], v[154:155] op_sel:[0,1,0]
	v_pk_fma_f32 v[156:157], v[196:197], v[238:239], v[156:157] op_sel:[0,1,0]
	v_pk_fma_f32 v[158:159], v[198:199], v[238:239], v[158:159] op_sel:[0,1,0]
	v_pk_fma_f32 v[160:161], v[200:201], v[238:239], v[160:161] op_sel:[0,1,0]
	v_pk_fma_f32 v[162:163], v[202:203], v[238:239], v[162:163] op_sel:[0,1,0]
	v_pk_fma_f32 v[164:165], v[204:205], v[238:239], v[164:165] op_sel:[0,1,0]
	ds_read2st64_b32 v[238:239], v231 offset0:224 offset1:228
	s_waitcnt lgkmcnt(4)
; #define LAS __attribute__((address_space(3)))
;     static __device__ __forceinline__ void run(float (&acc)[32], const float (&wv)[31], const LAS float* U, int rb, int cch) {
;         const float uv = U[ring94(ring94(rb + S)) * 256 + cch];
; #pragma unroll
;         for (int o = 0; o < 32; ++o) { constexpr int dummy = 0; const int kk = S - o + dummy; if (kk >= 0 && kk <= 30) acc[o] += wv[kk] * uv; }
; __device__ __forceinline__ void conv_loop(unsigned char* ws_, const float* const* in_, int l_, LAS unsigned char* lds, int tid, int bid, int G) {
;     ...
;             __syncthreads();
; #pragma unroll
;             for (int o = 0; o < 32; ++o) U[ring94(ring94(rb + o)) * 256 + cch] = acc[o];
	v_pk_fma_f32 v[152:153], v[72:73], v[240:241], v[152:153] op_sel_hi:[1,0,1]
	v_pk_fma_f32 v[154:155], v[74:75], v[240:241], v[154:155] op_sel_hi:[1,0,1]
	v_pk_fma_f32 v[156:157], v[76:77], v[240:241], v[156:157] op_sel_hi:[1,0,1]
	v_pk_fma_f32 v[158:159], v[78:79], v[240:241], v[158:159] op_sel_hi:[1,0,1]
	v_pk_fma_f32 v[160:161], v[80:81], v[240:241], v[160:161] op_sel_hi:[1,0,1]
	v_pk_fma_f32 v[162:163], v[82:83], v[240:241], v[162:163] op_sel_hi:[1,0,1]
	v_pk_fma_f32 v[164:165], v[84:85], v[240:241], v[164:165] op_sel_hi:[1,0,1]
	v_fmac_f32_e32 v153, v72, v241
	v_pk_fma_f32 v[154:155], v[192:193], v[240:241], v[154:155] op_sel:[0,1,0]
	v_pk_fma_f32 v[156:157], v[194:195], v[240:241], v[156:157] op_sel:[0,1,0]
	v_pk_fma_f32 v[158:159], v[196:197], v[240:241], v[158:159] op_sel:[0,1,0]
	v_pk_fma_f32 v[160:161], v[198:199], v[240:241], v[160:161] op_sel:[0,1,0]
	v_pk_fma_f32 v[162:163], v[200:201], v[240:241], v[162:163] op_sel:[0,1,0]
	v_pk_fma_f32 v[164:165], v[202:203], v[240:241], v[164:165] op_sel:[0,1,0]
	ds_read2st64_b32 v[240:241], v231 offset0:232 offset1:236
	s_waitcnt lgkmcnt(4)
	v_pk_fma_f32 v[154:155], v[72:73], v[232:233], v[154:155] op_sel_hi:[1,0,1]
	v_pk_fma_f32 v[156:157], v[74:75], v[232:233], v[156:157] op_sel_hi:[1,0,1]
	v_pk_fma_f32 v[158:159], v[76:77], v[232:233], v[158:159] op_sel_hi:[1,0,1]
	v_pk_fma_f32 v[160:161], v[78:79], v[232:233], v[160:161] op_sel_hi:[1,0,1]
	v_pk_fma_f32 v[162:163], v[80:81], v[232:233], v[162:163] op_sel_hi:[1,0,1]
	v_pk_fma_f32 v[164:165], v[82:83], v[232:233], v[164:165] op_sel_hi:[1,0,1]
	v_fmac_f32_e32 v155, v72, v233
	v_pk_fma_f32 v[156:157], v[192:193], v[232:233], v[156:157] op_sel:[0,1,0]
	v_pk_fma_f32 v[158:159], v[194:195], v[232:233], v[158:159] op_sel:[0,1,0]
	v_pk_fma_f32 v[160:161], v[196:197], v[232:233], v[160:161] op_sel:[0,1,0]
	v_pk_fma_f32 v[162:163], v[198:199], v[232:233], v[162:163] op_sel:[0,1,0]
	v_pk_fma_f32 v[164:165], v[200:201], v[232:233], v[164:165] op_sel:[0,1,0]
	ds_read2st64_b32 v[232:233], v231 offset0:240 offset1:244
	s_waitcnt lgkmcnt(4)
	v_pk_fma_f32 v[156:157], v[72:73], v[234:235], v[156:157] op_sel_hi:[1,0,1]
	v_pk_fma_f32 v[158:159], v[74:75], v[234:235], v[158:159] op_sel_hi:[1,0,1]
	v_pk_fma_f32 v[160:161], v[76:77], v[234:235], v[160:161] op_sel_hi:[1,0,1]
	v_pk_fma_f32 v[162:163], v[78:79], v[234:235], v[162:163] op_sel_hi:[1,0,1]
	v_pk_fma_f32 v[164:165], v[80:81], v[234:235], v[164:165] op_sel_hi:[1,0,1]
	v_fmac_f32_e32 v157, v72, v235
	v_pk_fma_f32 v[158:159], v[192:193], v[234:235], v[158:159] op_sel:[0,1,0]
	v_pk_fma_f32 v[160:161], v[194:195], v[234:235], v[160:161] op_sel:[0,1,0]
	v_pk_fma_f32 v[162:163], v[196:197], v[234:235], v[162:163] op_sel:[0,1,0]
	v_pk_fma_f32 v[164:165], v[198:199], v[234:235], v[164:165] op_sel:[0,1,0]
	s_waitcnt lgkmcnt(3)
	v_pk_fma_f32 v[158:159], v[72:73], v[236:237], v[158:159] op_sel_hi:[1,0,1]
	v_pk_fma_f32 v[160:161], v[74:75], v[236:237], v[160:161] op_sel_hi:[1,0,1]
	v_pk_fma_f32 v[162:163], v[76:77], v[236:237], v[162:163] op_sel_hi:[1,0,1]
	v_pk_fma_f32 v[164:165], v[78:79], v[236:237], v[164:165] op_sel_hi:[1,0,1]
	v_fmac_f32_e32 v159, v72, v237
	v_pk_fma_f32 v[160:161], v[192:193], v[236:237], v[160:161] op_sel:[0,1,0]
	v_pk_fma_f32 v[162:163], v[194:195], v[236:237], v[162:163] op_sel:[0,1,0]
	v_pk_fma_f32 v[164:165], v[196:197], v[236:237], v[164:165] op_sel:[0,1,0]
	s_waitcnt lgkmcnt(2)
	v_pk_fma_f32 v[160:161], v[72:73], v[238:239], v[160:161] op_sel_hi:[1,0,1]
	v_pk_fma_f32 v[162:163], v[74:75], v[238:239], v[162:163] op_sel_hi:[1,0,1]
	v_pk_fma_f32 v[164:165], v[76:77], v[238:239], v[164:165] op_sel_hi:[1,0,1]
	v_fmac_f32_e32 v161, v72, v239
	v_pk_fma_f32 v[162:163], v[192:193], v[238:239], v[162:163] op_sel:[0,1,0]
	v_pk_fma_f32 v[164:165], v[194:195], v[238:239], v[164:165] op_sel:[0,1,0]
	s_waitcnt lgkmcnt(1)
	v_pk_fma_f32 v[162:163], v[72:73], v[240:241], v[162:163] op_sel_hi:[1,0,1]
	v_pk_fma_f32 v[164:165], v[74:75], v[240:241], v[164:165] op_sel_hi:[1,0,1]
	v_fmac_f32_e32 v163, v72, v241
	v_pk_fma_f32 v[164:165], v[192:193], v[240:241], v[164:165] op_sel:[0,1,0]
	s_waitcnt lgkmcnt(0)
	v_pk_fma_f32 v[164:165], v[72:73], v[232:233], v[164:165] op_sel_hi:[1,0,1]
	v_fmac_f32_e32 v165, v72, v233
	ds_read_b32 v214, v230 offset:0
	ds_read_b32 v215, v230 offset:1024
	ds_read_b32 v216, v230 offset:2048
	ds_read_b32 v217, v230 offset:3072
	ds_read_b32 v218, v230 offset:4096
	ds_read_b32 v219, v230 offset:5120
	ds_read_b32 v220, v230 offset:6144
	ds_read_b32 v221, v230 offset:7168
	ds_read_b32 v222, v230 offset:8192
	ds_read_b32 v223, v230 offset:9216
	ds_read_b32 v224, v230 offset:10240
	ds_read_b32 v225, v230 offset:11264
	ds_read_b32 v226, v230 offset:12288
	ds_read_b32 v227, v230 offset:13312
	ds_read_b32 v228, v230 offset:14336
	s_barrier
	ds_write_b32 v231, v124 offset:0
	ds_write_b32 v231, v125 offset:1024
	ds_write_b32 v231, v126 offset:2048
	ds_write_b32 v231, v127 offset:3072
	ds_write_b32 v231, v128 offset:4096
	ds_write_b32 v231, v129 offset:5120
	ds_write_b32 v231, v130 offset:6144
	ds_write_b32 v231, v131 offset:7168
	ds_write_b32 v231, v132 offset:8192
	ds_write_b32 v231, v133 offset:9216
	ds_write_b32 v231, v134 offset:10240
	ds_write_b32 v231, v135 offset:11264
	ds_write_b32 v231, v136 offset:12288
	ds_write_b32 v231, v137 offset:13312
	ds_write_b32 v231, v148 offset:14336
	ds_write_b32 v231, v149 offset:15360
	ds_write_b32 v231, v150 offset:16384
	ds_write_b32 v231, v151 offset:17408
	ds_write_b32 v231, v152 offset:18432
	ds_write_b32 v231, v153 offset:19456
	ds_write_b32 v231, v154 offset:20480
	ds_write_b32 v231, v155 offset:21504
	ds_write_b32 v231, v156 offset:22528
	ds_write_b32 v231, v157 offset:23552
	ds_write_b32 v231, v158 offset:24576
	ds_write_b32 v231, v159 offset:25600
	ds_write_b32 v231, v160 offset:26624
	ds_write_b32 v231, v161 offset:27648
	ds_write_b32 v231, v162 offset:28672
	ds_write_b32 v231, v163 offset:29696
	ds_write_b32 v231, v164 offset:30720
	ds_write_b32 v231, v165 offset:31744
	v_add_u32_e32 v63, s26, v52
	v_cmp_lt_i32_e32 vcc, s91, v63
	v_lshlrev_b32_e32 v63, 10, v63
	v_add_u32_e32 v70, 0xfffe8800, v63
	v_cndmask_b32_e32 v63, v63, v70, vcc
	v_add_u32_e32 v63, v105, v63
	s_waitcnt lgkmcnt(0)
	s_barrier
; #define LAS __attribute__((address_space(3)))
; __device__ __forceinline__ void conv_loop(unsigned char* ws_, const float* const* in_, int l_, LAS unsigned char* lds, int tid, int bid, int G) {
;     ...
;             for (int i = 0; i < 8; ++i) { const int tok = 8 * w + i; f32x4 v = *(LAS f32x4*)(U + ring94(base + tok) * 256 + 4 * lane);
;                 const float mean = wave_sum((v[0] + v[1]) + (v[2] + v[3])) * (1.0f / 256.0f);
	v_lshl_add_u32 v188, v52, 10, v105
	ds_read_b128 v[124:127], v188 offset:0
	ds_read_b128 v[128:131], v188 offset:1024
	ds_read_b128 v[132:135], v188 offset:2048
	ds_read_b128 v[148:151], v188 offset:3072
	ds_read_b128 v[152:155], v188 offset:4096
	ds_read_b128 v[156:159], v188 offset:5120
	ds_read_b128 v[160:163], v188 offset:6144
	ds_read_b128 v[164:167], v188 offset:7168
	s_mov_b32 s76, 0x1000
	s_mov_b32 s77, 0
	v_lshl_add_u64 v[206:207], v[48:49], 0, s[42:43]
	v_lshl_add_u64 v[48:49], v[48:49], 0, s[74:75]
	v_lshl_add_u64 v[44:45], v[44:45], 0, s[74:75]
	v_lshl_add_u64 v[42:43], v[42:43], 0, s[74:75]
	v_lshl_add_u64 v[208:209], v[206:207], 0, s[76:77]
	v_lshl_add_u64 v[210:211], v[208:209], 0, s[76:77]
	v_lshl_add_u64 v[212:213], v[210:211], 0, s[76:77]
	s_add_i32 s27, s27, -1
	s_waitcnt lgkmcnt(7)
	v_add_f32_e32 v168, v125, v124
	v_add_f32_e32 v194, v126, v127
	s_waitcnt lgkmcnt(6)
	v_add_f32_e32 v169, v129, v128
	v_add_f32_e32 v195, v130, v131
	s_waitcnt lgkmcnt(5)
	v_add_f32_e32 v170, v133, v132
	v_add_f32_e32 v196, v134, v135
	s_waitcnt lgkmcnt(4)
	v_add_f32_e32 v171, v149, v148
	v_add_f32_e32 v197, v150, v151
	s_waitcnt lgkmcnt(3)
	v_add_f32_e32 v172, v153, v152
	v_add_f32_e32 v198, v154, v155
	s_waitcnt lgkmcnt(2)
	v_add_f32_e32 v173, v157, v156
	v_add_f32_e32 v199, v158, v159
	s_waitcnt lgkmcnt(1)
	v_add_f32_e32 v192, v161, v160
	v_add_f32_e32 v200, v162, v163
	s_waitcnt lgkmcnt(0)
	v_add_f32_e32 v193, v165, v164
	v_add_f32_e32 v201, v166, v167
	v_add_f32_e32 v168, v168, v194
	v_add_f32_e32 v169, v169, v195
	v_add_f32_e32 v170, v170, v196
	v_add_f32_e32 v171, v171, v197
	v_add_f32_e32 v172, v172, v198
	v_add_f32_e32 v173, v173, v199
	v_add_f32_e32 v192, v192, v200
	v_add_f32_e32 v193, v193, v201
	v_add_f32_dpp v168, v168, v168 quad_perm:[1,0,3,2] row_mask:0xf bank_mask:0xf
	v_add_f32_dpp v169, v169, v169 quad_perm:[1,0,3,2] row_mask:0xf bank_mask:0xf
	v_add_f32_dpp v170, v170, v170 quad_perm:[1,0,3,2] row_mask:0xf bank_mask:0xf
	v_add_f32_dpp v171, v171, v171 quad_perm:[1,0,3,2] row_mask:0xf bank_mask:0xf
	v_add_f32_dpp v172, v172, v172 quad_perm:[1,0,3,2] row_mask:0xf bank_mask:0xf
	v_add_f32_dpp v173, v173, v173 quad_perm:[1,0,3,2] row_mask:0xf bank_mask:0xf
	v_add_f32_dpp v192, v192, v192 quad_perm:[1,0,3,2] row_mask:0xf bank_mask:0xf
	v_add_f32_dpp v193, v193, v193 quad_perm:[1,0,3,2] row_mask:0xf bank_mask:0xf
	v_add_f32_dpp v168, v168, v168 quad_perm:[2,3,0,1] row_mask:0xf bank_mask:0xf
	v_add_f32_dpp v169, v169, v169 quad_perm:[2,3,0,1] row_mask:0xf bank_mask:0xf
	v_add_f32_dpp v170, v170, v170 quad_perm:[2,3,0,1] row_mask:0xf bank_mask:0xf
	v_add_f32_dpp v171, v171, v171 quad_perm:[2,3,0,1] row_mask:0xf bank_mask:0xf
	v_add_f32_dpp v172, v172, v172 quad_perm:[2,3,0,1] row_mask:0xf bank_mask:0xf
	v_add_f32_dpp v173, v173, v173 quad_perm:[2,3,0,1] row_mask:0xf bank_mask:0xf
	v_add_f32_dpp v192, v192, v192 quad_perm:[2,3,0,1] row_mask:0xf bank_mask:0xf
	v_add_f32_dpp v193, v193, v193 quad_perm:[2,3,0,1] row_mask:0xf bank_mask:0xf
	v_add_f32_dpp v168, v168, v168 row_half_mirror row_mask:0xf bank_mask:0xf
	v_add_f32_dpp v169, v169, v169 row_half_mirror row_mask:0xf bank_mask:0xf
	v_add_f32_dpp v170, v170, v170 row_half_mirror row_mask:0xf bank_mask:0xf
	v_add_f32_dpp v171, v171, v171 row_half_mirror row_mask:0xf bank_mask:0xf
	v_add_f32_dpp v172, v172, v172 row_half_mirror row_mask:0xf bank_mask:0xf
	v_add_f32_dpp v173, v173, v173 row_half_mirror row_mask:0xf bank_mask:0xf
	v_add_f32_dpp v192, v192, v192 row_half_mirror row_mask:0xf bank_mask:0xf
	v_add_f32_dpp v193, v193, v193 row_half_mirror row_mask:0xf bank_mask:0xf
	v_add_f32_dpp v168, v168, v168 row_mirror row_mask:0xf bank_mask:0xf
	v_add_f32_dpp v169, v169, v169 row_mirror row_mask:0xf bank_mask:0xf
	v_add_f32_dpp v170, v170, v170 row_mirror row_mask:0xf bank_mask:0xf
	v_add_f32_dpp v171, v171, v171 row_mirror row_mask:0xf bank_mask:0xf
	v_add_f32_dpp v172, v172, v172 row_mirror row_mask:0xf bank_mask:0xf
	v_add_f32_dpp v173, v173, v173 row_mirror row_mask:0xf bank_mask:0xf
	v_add_f32_dpp v192, v192, v192 row_mirror row_mask:0xf bank_mask:0xf
	v_add_f32_dpp v193, v193, v193 row_mirror row_mask:0xf bank_mask:0xf
	ds_bpermute_b32 v194, v110, v168
	ds_bpermute_b32 v195, v110, v169
	ds_bpermute_b32 v196, v110, v170
	ds_bpermute_b32 v197, v110, v171
	ds_bpermute_b32 v198, v110, v172
	ds_bpermute_b32 v199, v110, v173
	ds_bpermute_b32 v200, v110, v192
	ds_bpermute_b32 v201, v110, v193
	s_waitcnt lgkmcnt(7)
	v_add_f32_e32 v168, v168, v194
	s_waitcnt lgkmcnt(6)
	v_add_f32_e32 v169, v169, v195
	s_waitcnt lgkmcnt(5)
	v_add_f32_e32 v170, v170, v196
	s_waitcnt lgkmcnt(4)
	v_add_f32_e32 v171, v171, v197
	s_waitcnt lgkmcnt(3)
	v_add_f32_e32 v172, v172, v198
	s_waitcnt lgkmcnt(2)
	v_add_f32_e32 v173, v173, v199
	s_waitcnt lgkmcnt(1)
	v_add_f32_e32 v192, v192, v200
	s_waitcnt lgkmcnt(0)
	v_add_f32_e32 v193, v193, v201
	ds_bpermute_b32 v194, v111, v168
	ds_bpermute_b32 v195, v111, v169
	ds_bpermute_b32 v196, v111, v170
	ds_bpermute_b32 v197, v111, v171
	ds_bpermute_b32 v198, v111, v172
	ds_bpermute_b32 v199, v111, v173
	ds_bpermute_b32 v200, v111, v192
	ds_bpermute_b32 v201, v111, v193
	s_waitcnt lgkmcnt(7)
	v_add_f32_e32 v168, v168, v194
	s_waitcnt lgkmcnt(6)
	v_add_f32_e32 v169, v169, v195
	s_waitcnt lgkmcnt(5)
	v_add_f32_e32 v170, v170, v196
	s_waitcnt lgkmcnt(4)
	v_add_f32_e32 v171, v171, v197
	s_waitcnt lgkmcnt(3)
	v_add_f32_e32 v172, v172, v198
	s_waitcnt lgkmcnt(2)
	v_add_f32_e32 v173, v173, v199
	s_waitcnt lgkmcnt(1)
	v_add_f32_e32 v192, v192, v200
	s_waitcnt lgkmcnt(0)
; __device__ __forceinline__ void conv_loop(unsigned char* ws_, const float* const* in_, int l_, LAS unsigned char* lds, int tid, int bid, int G) {
;     ...
;                 const float mean = wave_sum((v[0] + v[1]) + (v[2] + v[3])) * (1.0f / 256.0f);
;                 v = v - mean; const float var = wave_sum((v[0] * v[0] + v[1] * v[1]) + (v[2] * v[2] + v[3] * v[3])) * (1.0f / 256.0f);
	v_add_f32_e32 v193, v193, v201
	v_fmamk_f32 v124, v168, 0xbb800000, v124
	v_fmamk_f32 v125, v168, 0xbb800000, v125
	v_fmamk_f32 v126, v168, 0xbb800000, v126
	v_fmamk_f32 v127, v168, 0xbb800000, v127
	v_fmamk_f32 v128, v169, 0xbb800000, v128
	v_fmamk_f32 v129, v169, 0xbb800000, v129
	v_fmamk_f32 v130, v169, 0xbb800000, v130
	v_fmamk_f32 v131, v169, 0xbb800000, v131
	v_fmamk_f32 v132, v170, 0xbb800000, v132
	v_fmamk_f32 v133, v170, 0xbb800000, v133
	v_fmamk_f32 v134, v170, 0xbb800000, v134
	v_fmamk_f32 v135, v170, 0xbb800000, v135
	v_fmamk_f32 v148, v171, 0xbb800000, v148
	v_fmamk_f32 v149, v171, 0xbb800000, v149
	v_fmamk_f32 v150, v171, 0xbb800000, v150
	v_fmamk_f32 v151, v171, 0xbb800000, v151
	v_fmamk_f32 v152, v172, 0xbb800000, v152
	v_fmamk_f32 v153, v172, 0xbb800000, v153
	v_fmamk_f32 v154, v172, 0xbb800000, v154
	v_fmamk_f32 v155, v172, 0xbb800000, v155
	v_fmamk_f32 v156, v173, 0xbb800000, v156
	v_fmamk_f32 v157, v173, 0xbb800000, v157
	v_fmamk_f32 v158, v173, 0xbb800000, v158
	v_fmamk_f32 v159, v173, 0xbb800000, v159
	v_fmamk_f32 v160, v192, 0xbb800000, v160
	v_fmamk_f32 v161, v192, 0xbb800000, v161
	v_fmamk_f32 v162, v192, 0xbb800000, v162
	v_fmamk_f32 v163, v192, 0xbb800000, v163
	v_fmamk_f32 v164, v193, 0xbb800000, v164
	v_fmamk_f32 v165, v193, 0xbb800000, v165
	v_fmamk_f32 v166, v193, 0xbb800000, v166
	v_fmamk_f32 v167, v193, 0xbb800000, v167
	v_mul_f32_e32 v168, v125, v125
	v_mul_f32_e32 v194, v124, v124
	v_mul_f32_e32 v169, v129, v129
	v_mul_f32_e32 v195, v128, v128
	v_mul_f32_e32 v170, v133, v133
	v_mul_f32_e32 v196, v132, v132
	v_mul_f32_e32 v171, v149, v149
	v_mul_f32_e32 v197, v148, v148
	v_mul_f32_e32 v172, v153, v153
	v_mul_f32_e32 v198, v152, v152
	v_mul_f32_e32 v173, v157, v157
	v_mul_f32_e32 v199, v156, v156
	v_mul_f32_e32 v192, v161, v161
	v_mul_f32_e32 v200, v160, v160
	v_mul_f32_e32 v193, v165, v165
	v_mul_f32_e32 v201, v164, v164
	v_add_f32_e32 v168, v168, v194
	v_add_f32_e32 v169, v169, v195
	v_add_f32_e32 v170, v170, v196
	v_add_f32_e32 v171, v171, v197
	v_add_f32_e32 v172, v172, v198
	v_add_f32_e32 v173, v173, v199
	v_add_f32_e32 v192, v192, v200
	v_add_f32_e32 v193, v193, v201
	v_mul_f32_e32 v194, v126, v126
	v_mul_f32_e32 v195, v130, v130
	v_mul_f32_e32 v196, v134, v134
	v_mul_f32_e32 v197, v150, v150
	v_mul_f32_e32 v198, v154, v154
	v_mul_f32_e32 v199, v158, v158
	v_mul_f32_e32 v200, v162, v162
	v_mul_f32_e32 v201, v166, v166
	v_mul_f32_e32 v202, v127, v127
	v_mul_f32_e32 v203, v131, v131
	v_mul_f32_e32 v204, v135, v135
	v_mul_f32_e32 v205, v151, v151
	v_add_f32_e32 v194, v194, v202
	v_add_f32_e32 v195, v195, v203
	v_add_f32_e32 v196, v196, v204
	v_add_f32_e32 v197, v197, v205
	v_mul_f32_e32 v202, v155, v155
	v_mul_f32_e32 v203, v159, v159
	v_mul_f32_e32 v204, v163, v163
	v_mul_f32_e32 v205, v167, v167
	v_add_f32_e32 v198, v198, v202
	v_add_f32_e32 v199, v199, v203
	v_add_f32_e32 v200, v200, v204
	v_add_f32_e32 v201, v201, v205
	v_add_f32_e32 v168, v168, v194
	v_add_f32_e32 v169, v169, v195
	v_add_f32_e32 v170, v170, v196
	v_add_f32_e32 v171, v171, v197
	v_add_f32_e32 v172, v172, v198
	v_add_f32_e32 v173, v173, v199
	v_add_f32_e32 v192, v192, v200
	v_add_f32_e32 v193, v193, v201
	v_add_f32_dpp v168, v168, v168 quad_perm:[1,0,3,2] row_mask:0xf bank_mask:0xf
	v_add_f32_dpp v169, v169, v169 quad_perm:[1,0,3,2] row_mask:0xf bank_mask:0xf
	v_add_f32_dpp v170, v170, v170 quad_perm:[1,0,3,2] row_mask:0xf bank_mask:0xf
	v_add_f32_dpp v171, v171, v171 quad_perm:[1,0,3,2] row_mask:0xf bank_mask:0xf
	v_add_f32_dpp v172, v172, v172 quad_perm:[1,0,3,2] row_mask:0xf bank_mask:0xf
	v_add_f32_dpp v173, v173, v173 quad_perm:[1,0,3,2] row_mask:0xf bank_mask:0xf
	v_add_f32_dpp v192, v192, v192 quad_perm:[1,0,3,2] row_mask:0xf bank_mask:0xf
	v_add_f32_dpp v193, v193, v193 quad_perm:[1,0,3,2] row_mask:0xf bank_mask:0xf
	v_add_f32_dpp v168, v168, v168 quad_perm:[2,3,0,1] row_mask:0xf bank_mask:0xf
	v_add_f32_dpp v169, v169, v169 quad_perm:[2,3,0,1] row_mask:0xf bank_mask:0xf
	v_add_f32_dpp v170, v170, v170 quad_perm:[2,3,0,1] row_mask:0xf bank_mask:0xf
	v_add_f32_dpp v171, v171, v171 quad_perm:[2,3,0,1] row_mask:0xf bank_mask:0xf
	v_add_f32_dpp v172, v172, v172 quad_perm:[2,3,0,1] row_mask:0xf bank_mask:0xf
	v_add_f32_dpp v173, v173, v173 quad_perm:[2,3,0,1] row_mask:0xf bank_mask:0xf
	v_add_f32_dpp v192, v192, v192 quad_perm:[2,3,0,1] row_mask:0xf bank_mask:0xf
	v_add_f32_dpp v193, v193, v193 quad_perm:[2,3,0,1] row_mask:0xf bank_mask:0xf
	v_add_f32_dpp v168, v168, v168 row_half_mirror row_mask:0xf bank_mask:0xf
	v_add_f32_dpp v169, v169, v169 row_half_mirror row_mask:0xf bank_mask:0xf
	v_add_f32_dpp v170, v170, v170 row_half_mirror row_mask:0xf bank_mask:0xf
	v_add_f32_dpp v171, v171, v171 row_half_mirror row_mask:0xf bank_mask:0xf
	v_add_f32_dpp v172, v172, v172 row_half_mirror row_mask:0xf bank_mask:0xf
	v_add_f32_dpp v173, v173, v173 row_half_mirror row_mask:0xf bank_mask:0xf
	v_add_f32_dpp v192, v192, v192 row_half_mirror row_mask:0xf bank_mask:0xf
	v_add_f32_dpp v193, v193, v193 row_half_mirror row_mask:0xf bank_mask:0xf
	v_add_f32_dpp v168, v168, v168 row_mirror row_mask:0xf bank_mask:0xf
	v_add_f32_dpp v169, v169, v169 row_mirror row_mask:0xf bank_mask:0xf
	v_add_f32_dpp v170, v170, v170 row_mirror row_mask:0xf bank_mask:0xf
	v_add_f32_dpp v171, v171, v171 row_mirror row_mask:0xf bank_mask:0xf
	v_add_f32_dpp v172, v172, v172 row_mirror row_mask:0xf bank_mask:0xf
	v_add_f32_dpp v173, v173, v173 row_mirror row_mask:0xf bank_mask:0xf
	v_add_f32_dpp v192, v192, v192 row_mirror row_mask:0xf bank_mask:0xf
	v_add_f32_dpp v193, v193, v193 row_mirror row_mask:0xf bank_mask:0xf
	ds_bpermute_b32 v194, v110, v168
	ds_bpermute_b32 v195, v110, v169
	ds_bpermute_b32 v196, v110, v170
	ds_bpermute_b32 v197, v110, v171
	ds_bpermute_b32 v198, v110, v172
	ds_bpermute_b32 v199, v110, v173
	ds_bpermute_b32 v200, v110, v192
	ds_bpermute_b32 v201, v110, v193
	s_waitcnt lgkmcnt(7)
; __device__ __forceinline__ float sigmoidf_(float x) { return __builtin_amdgcn_rcpf(1.f + __expf(-x)); }
; __device__ __forceinline__ void conv_loop(unsigned char* ws_, const float* const* in_, int l_, LAS unsigned char* lds, int tid, int bid, int G) {
;     ...
;                 v = v - mean; const float var = wave_sum((v[0] * v[0] + v[1] * v[1]) + (v[2] * v[2] + v[3] * v[3])) * (1.0f / 256.0f);
;                 const float rstd = rsqrtf(var + LN_EPS); f32x4 y = v * rstd * gg + bb;
; #pragma unroll
;                 for (int e = 0; e < 4; ++e) y[e] = y[e] * sigmoidf_(y[e]);
	v_add_f32_e32 v168, v168, v194
	s_waitcnt lgkmcnt(6)
	v_add_f32_e32 v169, v169, v195
	s_waitcnt lgkmcnt(5)
	v_add_f32_e32 v170, v170, v196
	s_waitcnt lgkmcnt(4)
	v_add_f32_e32 v171, v171, v197
	s_waitcnt lgkmcnt(3)
	v_add_f32_e32 v172, v172, v198
	s_waitcnt lgkmcnt(2)
	v_add_f32_e32 v173, v173, v199
	s_waitcnt lgkmcnt(1)
	v_add_f32_e32 v192, v192, v200
	s_waitcnt lgkmcnt(0)
	v_add_f32_e32 v193, v193, v201
	ds_bpermute_b32 v194, v111, v168
	ds_bpermute_b32 v195, v111, v169
	ds_bpermute_b32 v196, v111, v170
	ds_bpermute_b32 v197, v111, v171
	ds_bpermute_b32 v198, v111, v172
	ds_bpermute_b32 v199, v111, v173
	ds_bpermute_b32 v200, v111, v192
	ds_bpermute_b32 v201, v111, v193
	s_waitcnt lgkmcnt(7)
	v_add_f32_e32 v168, v168, v194
	s_waitcnt lgkmcnt(6)
	v_add_f32_e32 v169, v169, v195
	s_waitcnt lgkmcnt(5)
	v_add_f32_e32 v170, v170, v196
	s_waitcnt lgkmcnt(4)
	v_add_f32_e32 v171, v171, v197
	s_waitcnt lgkmcnt(3)
	v_add_f32_e32 v172, v172, v198
	s_waitcnt lgkmcnt(2)
	v_add_f32_e32 v173, v173, v199
	s_waitcnt lgkmcnt(1)
	v_add_f32_e32 v192, v192, v200
	s_waitcnt lgkmcnt(0)
	v_add_f32_e32 v193, v193, v201
	v_fmamk_f32 v168, v168, 0x3b800000, v176
	v_fmamk_f32 v169, v169, 0x3b800000, v176
	v_fmamk_f32 v170, v170, 0x3b800000, v176
	v_fmamk_f32 v171, v171, 0x3b800000, v176
	v_fmamk_f32 v172, v172, 0x3b800000, v176
	v_fmamk_f32 v173, v173, 0x3b800000, v176
	v_fmamk_f32 v192, v192, 0x3b800000, v176
	v_fmamk_f32 v193, v193, 0x3b800000, v176
	v_rsq_f32_e32 v168, v168
	v_rsq_f32_e32 v169, v169
	v_rsq_f32_e32 v170, v170
	v_rsq_f32_e32 v171, v171
	v_rsq_f32_e32 v172, v172
	v_rsq_f32_e32 v173, v173
	v_rsq_f32_e32 v192, v192
	v_rsq_f32_e32 v193, v193
	v_mul_f32_e32 v124, v124, v168
	v_mul_f32_e32 v125, v125, v168
	v_mul_f32_e32 v126, v126, v168
	v_mul_f32_e32 v127, v127, v168
	v_mul_f32_e32 v128, v128, v169
	v_mul_f32_e32 v129, v129, v169
	v_mul_f32_e32 v130, v130, v169
	v_mul_f32_e32 v131, v131, v169
	v_mul_f32_e32 v132, v132, v170
	v_mul_f32_e32 v133, v133, v170
	v_mul_f32_e32 v134, v134, v170
	v_mul_f32_e32 v135, v135, v170
	v_mul_f32_e32 v148, v148, v171
	v_mul_f32_e32 v149, v149, v171
	v_mul_f32_e32 v150, v150, v171
	v_mul_f32_e32 v151, v151, v171
	v_mul_f32_e32 v152, v152, v172
	v_mul_f32_e32 v153, v153, v172
	v_mul_f32_e32 v154, v154, v172
	v_mul_f32_e32 v155, v155, v172
	v_mul_f32_e32 v156, v156, v173
	v_mul_f32_e32 v157, v157, v173
	v_mul_f32_e32 v158, v158, v173
	v_mul_f32_e32 v159, v159, v173
	v_mul_f32_e32 v160, v160, v192
	v_mul_f32_e32 v161, v161, v192
	v_mul_f32_e32 v162, v162, v192
	v_mul_f32_e32 v163, v163, v192
	v_mul_f32_e32 v164, v164, v193
	v_mul_f32_e32 v165, v165, v193
	v_mul_f32_e32 v166, v166, v193
	v_mul_f32_e32 v167, v167, v193
	v_fma_f32 v124, v2, v124, v6
	v_fma_f32 v125, v3, v125, v7
	v_fma_f32 v126, v4, v126, v8
	v_fma_f32 v127, v5, v127, v9
	v_fma_f32 v128, v2, v128, v6
	v_fma_f32 v129, v3, v129, v7
	v_fma_f32 v130, v4, v130, v8
	v_fma_f32 v131, v5, v131, v9
	v_fma_f32 v132, v2, v132, v6
	v_fma_f32 v133, v3, v133, v7
	v_fma_f32 v134, v4, v134, v8
	v_fma_f32 v135, v5, v135, v9
	v_fma_f32 v148, v2, v148, v6
	v_fma_f32 v149, v3, v149, v7
	v_fma_f32 v150, v4, v150, v8
	v_fma_f32 v151, v5, v151, v9
	v_fma_f32 v152, v2, v152, v6
	v_fma_f32 v153, v3, v153, v7
	v_fma_f32 v154, v4, v154, v8
	v_fma_f32 v155, v5, v155, v9
	v_fma_f32 v156, v2, v156, v6
	v_fma_f32 v157, v3, v157, v7
	v_fma_f32 v158, v4, v158, v8
	v_fma_f32 v159, v5, v159, v9
	v_fma_f32 v160, v2, v160, v6
	v_fma_f32 v161, v3, v161, v7
	v_fma_f32 v162, v4, v162, v8
	v_fma_f32 v163, v5, v163, v9
	v_fma_f32 v164, v2, v164, v6
	v_fma_f32 v165, v3, v165, v7
	v_fma_f32 v166, v4, v166, v8
	v_fma_f32 v167, v5, v167, v9
	v_mul_f32_e32 v168, 0xbfb8aa3b, v124
	v_mul_f32_e32 v169, 0xbfb8aa3b, v125
	v_mul_f32_e32 v170, 0xbfb8aa3b, v126
	v_mul_f32_e32 v171, 0xbfb8aa3b, v127
	v_mul_f32_e32 v172, 0xbfb8aa3b, v128
	v_mul_f32_e32 v173, 0xbfb8aa3b, v129
	v_mul_f32_e32 v192, 0xbfb8aa3b, v130
	v_mul_f32_e32 v193, 0xbfb8aa3b, v131
	v_mul_f32_e32 v194, 0xbfb8aa3b, v132
	v_mul_f32_e32 v195, 0xbfb8aa3b, v133
	v_mul_f32_e32 v196, 0xbfb8aa3b, v134
	v_mul_f32_e32 v197, 0xbfb8aa3b, v135
	v_mul_f32_e32 v198, 0xbfb8aa3b, v148
	v_mul_f32_e32 v199, 0xbfb8aa3b, v149
	v_mul_f32_e32 v200, 0xbfb8aa3b, v150
	v_mul_f32_e32 v201, 0xbfb8aa3b, v151
	v_exp_f32_e32 v168, v168
	v_exp_f32_e32 v169, v169
	v_exp_f32_e32 v170, v170
	v_exp_f32_e32 v171, v171
	v_exp_f32_e32 v172, v172
	v_exp_f32_e32 v173, v173
	v_exp_f32_e32 v192, v192
	v_exp_f32_e32 v193, v193
	v_exp_f32_e32 v194, v194
	v_exp_f32_e32 v195, v195
	v_exp_f32_e32 v196, v196
	v_exp_f32_e32 v197, v197
	v_exp_f32_e32 v198, v198
	v_exp_f32_e32 v199, v199
	v_exp_f32_e32 v200, v200
	v_exp_f32_e32 v201, v201
	v_add_f32_e32 v168, 1.0, v168
	v_add_f32_e32 v169, 1.0, v169
	v_add_f32_e32 v170, 1.0, v170
	v_add_f32_e32 v171, 1.0, v171
	v_add_f32_e32 v172, 1.0, v172
	v_add_f32_e32 v173, 1.0, v173
	v_add_f32_e32 v192, 1.0, v192
	v_add_f32_e32 v193, 1.0, v193
	v_add_f32_e32 v194, 1.0, v194
	v_add_f32_e32 v195, 1.0, v195
	v_add_f32_e32 v196, 1.0, v196
	v_add_f32_e32 v197, 1.0, v197
	v_add_f32_e32 v198, 1.0, v198
	v_add_f32_e32 v199, 1.0, v199
; #define LAS __attribute__((address_space(3)))
; __device__ __forceinline__ unsigned cvt_pk_bf16(float lo, float hi) { unsigned r; asm volatile("v_cvt_pk_bf16_f32 %0, %1, %2" : "=v"(r) : "v"(lo), "v"(hi)); return r; }
; __device__ __forceinline__ float sigmoidf_(float x) { return __builtin_amdgcn_rcpf(1.f + __expf(-x)); }
; __device__ __forceinline__ void conv_loop(unsigned char* ws_, const float* const* in_, int l_, LAS unsigned char* lds, int tid, int bid, int G) {
;     ...
;             for (int i = 0; i < 4; ++i) { const int idx = tid + 512 * i; const int row = ring94(base + 30 + (idx >> 5)), ch = idx & 31; f32x4 u0, u1; conv_glu8(pa[i], pg[i], u0, u1);
;                 *(LAS f32x4*)(U + row * 256 + ch * 8) = u0; *(LAS f32x4*)(U + row * 256 + ch * 8 + 4) = u1; }
;     ...
;                 for (int e = 0; e < 4; ++e) y[e] = y[e] * sigmoidf_(y[e]);
;                 u32x2 wv2; wv2.x = cvt_pk_bf16(y[0], y[1]); wv2.y = cvt_pk_bf16(y[2], y[3]);
;                 *(u32x2*)(X.MIX + ((size_t)b * SEQ + t0 + tok) * DM + AW + 4 * lane) = wv2; }
;             __syncthreads();
;             base = ring94(base + 64);
	v_add_f32_e32 v200, 1.0, v200
	v_add_f32_e32 v201, 1.0, v201
	v_rcp_f32_e32 v168, v168
	v_rcp_f32_e32 v169, v169
	v_rcp_f32_e32 v170, v170
	v_rcp_f32_e32 v171, v171
	v_rcp_f32_e32 v172, v172
	v_rcp_f32_e32 v173, v173
	v_rcp_f32_e32 v192, v192
	v_rcp_f32_e32 v193, v193
	v_rcp_f32_e32 v194, v194
	v_rcp_f32_e32 v195, v195
	v_rcp_f32_e32 v196, v196
	v_rcp_f32_e32 v197, v197
	v_rcp_f32_e32 v198, v198
	v_rcp_f32_e32 v199, v199
	v_rcp_f32_e32 v200, v200
	v_rcp_f32_e32 v201, v201
	v_mul_f32_e32 v124, v124, v168
	v_mul_f32_e32 v125, v125, v169
	v_mul_f32_e32 v126, v126, v170
	v_mul_f32_e32 v127, v127, v171
	v_mul_f32_e32 v128, v128, v172
	v_mul_f32_e32 v129, v129, v173
	v_mul_f32_e32 v130, v130, v192
	v_mul_f32_e32 v131, v131, v193
	v_mul_f32_e32 v132, v132, v194
	v_mul_f32_e32 v133, v133, v195
	v_mul_f32_e32 v134, v134, v196
	v_mul_f32_e32 v135, v135, v197
	v_mul_f32_e32 v148, v148, v198
	v_mul_f32_e32 v149, v149, v199
	v_mul_f32_e32 v150, v150, v200
	v_mul_f32_e32 v151, v151, v201
	v_cvt_pk_bf16_f32 v124, v124, v125
	v_cvt_pk_bf16_f32 v125, v126, v127
	v_cvt_pk_bf16_f32 v128, v128, v129
	v_cvt_pk_bf16_f32 v129, v130, v131
	v_cvt_pk_bf16_f32 v132, v132, v133
	v_cvt_pk_bf16_f32 v133, v134, v135
	v_cvt_pk_bf16_f32 v148, v148, v149
	v_cvt_pk_bf16_f32 v149, v150, v151
	global_store_dwordx2 v[206:207], v[124:125], off
	global_store_dwordx2 v[206:207], v[128:129], off offset:2048
	global_store_dwordx2 v[208:209], v[132:133], off
	global_store_dwordx2 v[208:209], v[148:149], off offset:2048
	v_mul_f32_e32 v168, 0xbfb8aa3b, v152
	v_mul_f32_e32 v169, 0xbfb8aa3b, v153
	v_mul_f32_e32 v170, 0xbfb8aa3b, v154
	v_mul_f32_e32 v171, 0xbfb8aa3b, v155
	v_mul_f32_e32 v172, 0xbfb8aa3b, v156
	v_mul_f32_e32 v173, 0xbfb8aa3b, v157
	v_mul_f32_e32 v192, 0xbfb8aa3b, v158
	v_mul_f32_e32 v193, 0xbfb8aa3b, v159
	v_mul_f32_e32 v194, 0xbfb8aa3b, v160
	v_mul_f32_e32 v195, 0xbfb8aa3b, v161
	v_mul_f32_e32 v196, 0xbfb8aa3b, v162
	v_mul_f32_e32 v197, 0xbfb8aa3b, v163
	v_mul_f32_e32 v198, 0xbfb8aa3b, v164
	v_mul_f32_e32 v199, 0xbfb8aa3b, v165
	v_mul_f32_e32 v200, 0xbfb8aa3b, v166
	v_mul_f32_e32 v201, 0xbfb8aa3b, v167
	v_exp_f32_e32 v168, v168
	v_exp_f32_e32 v169, v169
	v_exp_f32_e32 v170, v170
	v_exp_f32_e32 v171, v171
	v_exp_f32_e32 v172, v172
	v_exp_f32_e32 v173, v173
	v_exp_f32_e32 v192, v192
	v_exp_f32_e32 v193, v193
	v_exp_f32_e32 v194, v194
	v_exp_f32_e32 v195, v195
	v_exp_f32_e32 v196, v196
	v_exp_f32_e32 v197, v197
	v_exp_f32_e32 v198, v198
	v_exp_f32_e32 v199, v199
	v_exp_f32_e32 v200, v200
	v_exp_f32_e32 v201, v201
	v_add_f32_e32 v168, 1.0, v168
	v_add_f32_e32 v169, 1.0, v169
	v_add_f32_e32 v170, 1.0, v170
	v_add_f32_e32 v171, 1.0, v171
	v_add_f32_e32 v172, 1.0, v172
	v_add_f32_e32 v173, 1.0, v173
	v_add_f32_e32 v192, 1.0, v192
	v_add_f32_e32 v193, 1.0, v193
	v_add_f32_e32 v194, 1.0, v194
	v_add_f32_e32 v195, 1.0, v195
	v_add_f32_e32 v196, 1.0, v196
	v_add_f32_e32 v197, 1.0, v197
	v_add_f32_e32 v198, 1.0, v198
	v_add_f32_e32 v199, 1.0, v199
	v_add_f32_e32 v200, 1.0, v200
	v_add_f32_e32 v201, 1.0, v201
	v_rcp_f32_e32 v168, v168
	v_rcp_f32_e32 v169, v169
	v_rcp_f32_e32 v170, v170
	v_rcp_f32_e32 v171, v171
	v_rcp_f32_e32 v172, v172
	v_rcp_f32_e32 v173, v173
	v_rcp_f32_e32 v192, v192
	v_rcp_f32_e32 v193, v193
	v_rcp_f32_e32 v194, v194
	v_rcp_f32_e32 v195, v195
	v_rcp_f32_e32 v196, v196
	v_rcp_f32_e32 v197, v197
	v_rcp_f32_e32 v198, v198
	v_rcp_f32_e32 v199, v199
	v_rcp_f32_e32 v200, v200
	v_rcp_f32_e32 v201, v201
	v_mul_f32_e32 v152, v152, v168
	v_mul_f32_e32 v153, v153, v169
	v_mul_f32_e32 v154, v154, v170
	v_mul_f32_e32 v155, v155, v171
	v_mul_f32_e32 v156, v156, v172
	v_mul_f32_e32 v157, v157, v173
	v_mul_f32_e32 v158, v158, v192
	v_mul_f32_e32 v159, v159, v193
	v_mul_f32_e32 v160, v160, v194
	v_mul_f32_e32 v161, v161, v195
	v_mul_f32_e32 v162, v162, v196
	v_mul_f32_e32 v163, v163, v197
	v_mul_f32_e32 v164, v164, v198
	v_mul_f32_e32 v165, v165, v199
	v_mul_f32_e32 v166, v166, v200
	v_mul_f32_e32 v167, v167, v201
	v_cvt_pk_bf16_f32 v152, v152, v153
	v_cvt_pk_bf16_f32 v153, v154, v155
	v_cvt_pk_bf16_f32 v156, v156, v157
	v_cvt_pk_bf16_f32 v157, v158, v159
	v_cvt_pk_bf16_f32 v160, v160, v161
	v_cvt_pk_bf16_f32 v161, v162, v163
	v_cvt_pk_bf16_f32 v164, v164, v165
	v_cvt_pk_bf16_f32 v165, v166, v167
	global_store_dwordx2 v[210:211], v[152:153], off
	global_store_dwordx2 v[210:211], v[156:157], off offset:2048
	global_store_dwordx2 v[212:213], v[160:161], off
	global_store_dwordx2 v[212:213], v[164:165], off offset:2048
	s_cmp_eq_u32 s27, 0
	s_barrier
	s_cbranch_scc1 .LBB0_292
	ds_write_b32 v229, v214 offset:0
	ds_write_b32 v229, v215 offset:1024
	ds_write_b32 v229, v216 offset:2048
	ds_write_b32 v229, v217 offset:3072
	ds_write_b32 v229, v218 offset:4096
	ds_write_b32 v229, v219 offset:5120
	ds_write_b32 v229, v220 offset:6144
	ds_write_b32 v229, v221 offset:7168
	ds_write_b32 v229, v222 offset:8192
	ds_write_b32 v229, v223 offset:9216
	ds_write_b32 v229, v224 offset:10240
	ds_write_b32 v229, v225 offset:11264
	ds_write_b32 v229, v226 offset:12288
	ds_write_b32 v229, v227 offset:13312
	ds_write_b32 v229, v228 offset:14336
